# row-stat publish: xor16/xor32 reductions via v_permlane16/32_swap instead of ds_bpermute (44 sites)
# speedup vs baseline: 1.0035x; 1.0035x over previous
;     __device__ __forceinline__ void publish(const f32x4 (&v)[2][2][4][2], const Unit& u, int wr, int wc, int fr, int fq, PG8_LAS unsigned char* lds, int wid, int lane) const {
;     ...
;                 float s = 0.f;
; #pragma unroll
;                 for (int bj = 0; bj < 2; ++bj)
; #pragma unroll
;                     for (int n = 0; n < 2; ++n) { const f32x4 x = v[ai][bj][m][n]; s += (x[0] * x[0] + x[1] * x[1]) + (x[2] * x[2] + x[3] * x[3]); }
;                 s += __shfl_xor(s, 16); s += __shfl_xor(s, 32);
;                 if (fq == 0) P[(ai * HALF + wr * 64 + m * 16 + fr) * 4 + wc] = s;
.LBB0_818:
	s_or_b64 exec, exec, s[0:1]
	v_mul_f32_e32 v130, v127, v127
	s_waitcnt lgkmcnt(0)
	v_mul_f32_e32 v131, v129, v129
	v_fmac_f32_e32 v130, v126, v126
	v_fmac_f32_e32 v131, v128, v128
	v_add_f32_e32 v130, v130, v131
	v_mul_f32_e32 v131, v123, v123
	v_mul_f32_e32 v132, v125, v125
	v_fmac_f32_e32 v131, v122, v122
	v_fmac_f32_e32 v132, v124, v124
	v_add_f32_e32 v131, v131, v132
	v_add_f32_e32 v130, v131, v130
	v_mul_f32_e32 v131, v115, v115
	v_mul_f32_e32 v132, v117, v117
	v_fmac_f32_e32 v131, v114, v114
	v_fmac_f32_e32 v132, v116, v116
	v_add_f32_e32 v131, v131, v132
	v_add_f32_e32 v130, v131, v130
	v_mul_f32_e32 v131, v119, v119
	v_mul_f32_e32 v132, v121, v121
	v_fmac_f32_e32 v131, v118, v118
	v_fmac_f32_e32 v132, v120, v120
	v_add_f32_e32 v131, v131, v132
	v_add_f32_e32 v130, v131, v130
	v_mov_b32_e32 v131, v130
	s_nop 1
	v_permlane16_swap_b32_e32 v130, v131
	v_add_f32_e32 v130, v130, v131
	v_mov_b32_e32 v131, v130
	s_nop 1
	v_permlane32_swap_b32_e32 v130, v131
	s_and_saveexec_b64 s[0:1], s[38:39]
	s_cbranch_execz .LBB0_820
	s_lshl_b32 s4, s31, 10
	s_add_i32 s4, s20, s4
	s_waitcnt lgkmcnt(0)
	v_add_f32_e32 v130, v130, v131
	v_lshl_add_u32 v131, v230, 4, s4
	ds_write_b32 v131, v130 offset:256
.LBB0_820:
	s_or_b64 exec, exec, s[0:1]
	v_mul_f32_e32 v130, v95, v95
	s_waitcnt lgkmcnt(0)
	v_mul_f32_e32 v131, v97, v97
	v_fmac_f32_e32 v130, v94, v94
	v_fmac_f32_e32 v131, v96, v96
	v_add_f32_e32 v130, v130, v131
	v_mul_f32_e32 v131, v91, v91
	v_mul_f32_e32 v132, v93, v93
	v_fmac_f32_e32 v131, v90, v90
	v_fmac_f32_e32 v132, v92, v92
	v_add_f32_e32 v131, v131, v132
	v_add_f32_e32 v130, v131, v130
	v_mul_f32_e32 v131, v87, v87
	v_mul_f32_e32 v132, v89, v89
	v_fmac_f32_e32 v131, v86, v86
	v_fmac_f32_e32 v132, v88, v88
	v_add_f32_e32 v131, v131, v132
	v_add_f32_e32 v130, v131, v130
	v_mul_f32_e32 v131, v83, v83
	v_mul_f32_e32 v132, v85, v85
	v_fmac_f32_e32 v131, v82, v82
	v_fmac_f32_e32 v132, v84, v84
	v_add_f32_e32 v131, v131, v132
	v_add_f32_e32 v130, v131, v130
	v_mov_b32_e32 v131, v130
	s_nop 1
	v_permlane16_swap_b32_e32 v130, v131
	v_add_f32_e32 v130, v130, v131
	v_mov_b32_e32 v131, v130
	s_nop 1
	v_permlane32_swap_b32_e32 v130, v131
	s_and_saveexec_b64 s[0:1], s[38:39]
	s_cbranch_execz .LBB0_822
	s_lshl_b32 s4, s31, 10
	s_add_i32 s4, s20, s4
	s_waitcnt lgkmcnt(0)
	v_add_f32_e32 v130, v130, v131
	v_lshl_add_u32 v131, v230, 4, s4
	ds_write_b32 v131, v130 offset:512
.LBB0_822:
	s_or_b64 exec, exec, s[0:1]
	v_mul_f32_e32 v130, v79, v79
	s_waitcnt lgkmcnt(0)
	v_mul_f32_e32 v131, v81, v81
	v_fmac_f32_e32 v130, v78, v78
	v_fmac_f32_e32 v131, v80, v80
	v_add_f32_e32 v130, v130, v131
	v_mul_f32_e32 v131, v75, v75
	v_mul_f32_e32 v132, v77, v77
	v_fmac_f32_e32 v131, v74, v74
	v_fmac_f32_e32 v132, v76, v76
	v_add_f32_e32 v131, v131, v132
	v_add_f32_e32 v130, v131, v130
	v_mul_f32_e32 v131, v71, v71
	v_mul_f32_e32 v132, v73, v73
	v_fmac_f32_e32 v131, v70, v70
	v_fmac_f32_e32 v132, v72, v72
	v_add_f32_e32 v131, v131, v132
	v_add_f32_e32 v130, v131, v130
	v_mul_f32_e32 v131, v67, v67
	v_mul_f32_e32 v132, v69, v69
	v_fmac_f32_e32 v131, v66, v66
	v_fmac_f32_e32 v132, v68, v68
	v_add_f32_e32 v131, v131, v132
	v_add_f32_e32 v130, v131, v130
	v_mov_b32_e32 v131, v130
	s_nop 1
	v_permlane16_swap_b32_e32 v130, v131
	v_add_f32_e32 v130, v130, v131
	v_mov_b32_e32 v131, v130
	s_nop 1
	v_permlane32_swap_b32_e32 v130, v131
	s_and_saveexec_b64 s[0:1], s[38:39]
	s_cbranch_execz .LBB0_824
	s_lshl_b32 s4, s31, 10
	s_add_i32 s4, s20, s4
	s_waitcnt lgkmcnt(0)
	v_add_f32_e32 v130, v130, v131
	v_lshl_add_u32 v131, v230, 4, s4
	ds_write_b32 v131, v130 offset:768
;     __device__ __forceinline__ void publish(const f32x4 (&v)[2][2][4][2], const Unit& u, int wr, int wc, int fr, int fq, PG8_LAS unsigned char* lds, int wid, int lane) const {
;     ...
;                 float s = 0.f;
; #pragma unroll
;                 for (int bj = 0; bj < 2; ++bj)
; #pragma unroll
;                     for (int n = 0; n < 2; ++n) { const f32x4 x = v[ai][bj][m][n]; s += (x[0] * x[0] + x[1] * x[1]) + (x[2] * x[2] + x[3] * x[3]); }
;                 s += __shfl_xor(s, 16); s += __shfl_xor(s, 32);
;                 if (fq == 0) P[(ai * HALF + wr * 64 + m * 16 + fr) * 4 + wc] = s;
.LBB0_824:
	s_or_b64 exec, exec, s[0:1]
	v_mul_f32_e32 v130, v63, v63
	s_waitcnt lgkmcnt(0)
	v_mul_f32_e32 v131, v65, v65
	v_fmac_f32_e32 v130, v62, v62
	v_fmac_f32_e32 v131, v64, v64
	v_add_f32_e32 v130, v130, v131
	v_mul_f32_e32 v131, v59, v59
	v_mul_f32_e32 v132, v61, v61
	v_fmac_f32_e32 v131, v58, v58
	v_fmac_f32_e32 v132, v60, v60
	v_add_f32_e32 v131, v131, v132
	v_add_f32_e32 v130, v131, v130
	v_mul_f32_e32 v131, v55, v55
	v_mul_f32_e32 v132, v57, v57
	v_fmac_f32_e32 v131, v54, v54
	v_fmac_f32_e32 v132, v56, v56
	v_add_f32_e32 v131, v131, v132
	v_add_f32_e32 v130, v131, v130
	v_mul_f32_e32 v131, v51, v51
	v_mul_f32_e32 v132, v53, v53
	v_fmac_f32_e32 v131, v50, v50
	v_fmac_f32_e32 v132, v52, v52
	v_add_f32_e32 v131, v131, v132
	v_add_f32_e32 v130, v131, v130
	v_mov_b32_e32 v131, v130
	s_nop 1
	v_permlane16_swap_b32_e32 v130, v131
	v_add_f32_e32 v130, v130, v131
	v_mov_b32_e32 v131, v130
	s_nop 1
	v_permlane32_swap_b32_e32 v130, v131
	s_and_saveexec_b64 s[0:1], s[38:39]
	s_cbranch_execz .LBB0_826
	s_lshl_b32 s4, s31, 10
	s_add_i32 s4, s20, s4
	s_waitcnt lgkmcnt(0)
	v_add_f32_e32 v130, v130, v131
	v_lshl_add_u32 v131, v230, 4, s4
	ds_write_b32 v131, v130 offset:2048
.LBB0_826:
	s_or_b64 exec, exec, s[0:1]
	v_mul_f32_e32 v130, v47, v47
	s_waitcnt lgkmcnt(0)
	v_mul_f32_e32 v131, v49, v49
	v_fmac_f32_e32 v130, v46, v46
	v_fmac_f32_e32 v131, v48, v48
	v_add_f32_e32 v130, v130, v131
	v_mul_f32_e32 v131, v43, v43
	v_mul_f32_e32 v132, v45, v45
	v_fmac_f32_e32 v131, v42, v42
	v_fmac_f32_e32 v132, v44, v44
	v_add_f32_e32 v131, v131, v132
	v_add_f32_e32 v130, v131, v130
	v_mul_f32_e32 v131, v39, v39
	v_mul_f32_e32 v132, v41, v41
	v_fmac_f32_e32 v131, v38, v38
	v_fmac_f32_e32 v132, v40, v40
	v_add_f32_e32 v131, v131, v132
	v_add_f32_e32 v130, v131, v130
	v_mul_f32_e32 v131, v35, v35
	v_mul_f32_e32 v132, v37, v37
	v_fmac_f32_e32 v131, v34, v34
	v_fmac_f32_e32 v132, v36, v36
	v_add_f32_e32 v131, v131, v132
	v_add_f32_e32 v130, v131, v130
	v_mov_b32_e32 v131, v130
	s_nop 1
	v_permlane16_swap_b32_e32 v130, v131
	v_add_f32_e32 v130, v130, v131
	v_mov_b32_e32 v131, v130
	s_nop 1
	v_permlane32_swap_b32_e32 v130, v131
	s_and_saveexec_b64 s[0:1], s[38:39]
	s_cbranch_execz .LBB0_828
	s_lshl_b32 s4, s31, 10
	s_add_i32 s4, s20, s4
	s_waitcnt lgkmcnt(0)
	v_add_f32_e32 v130, v130, v131
	v_lshl_add_u32 v131, v230, 4, s4
	ds_write_b32 v131, v130 offset:2304
.LBB0_828:
	s_or_b64 exec, exec, s[0:1]
	v_mul_f32_e32 v130, v31, v31
	s_waitcnt lgkmcnt(0)
	v_mul_f32_e32 v131, v33, v33
	v_fmac_f32_e32 v130, v30, v30
	v_fmac_f32_e32 v131, v32, v32
	v_add_f32_e32 v130, v130, v131
	v_mul_f32_e32 v131, v27, v27
	v_mul_f32_e32 v132, v29, v29
	v_fmac_f32_e32 v131, v26, v26
	v_fmac_f32_e32 v132, v28, v28
	v_add_f32_e32 v131, v131, v132
	v_add_f32_e32 v130, v131, v130
	v_mul_f32_e32 v131, v23, v23
	v_mul_f32_e32 v132, v25, v25
	v_fmac_f32_e32 v131, v22, v22
	v_fmac_f32_e32 v132, v24, v24
	v_add_f32_e32 v131, v131, v132
	v_add_f32_e32 v130, v131, v130
	v_mul_f32_e32 v131, v19, v19
	v_mul_f32_e32 v132, v21, v21
	v_fmac_f32_e32 v131, v18, v18
	v_fmac_f32_e32 v132, v20, v20
	v_add_f32_e32 v131, v131, v132
	v_add_f32_e32 v130, v131, v130
	v_mov_b32_e32 v131, v130
	s_nop 1
	v_permlane16_swap_b32_e32 v130, v131
	v_add_f32_e32 v130, v130, v131
	v_mov_b32_e32 v131, v130
	s_nop 1
	v_permlane32_swap_b32_e32 v130, v131
	s_and_saveexec_b64 s[0:1], s[38:39]
	s_cbranch_execz .LBB0_830
	s_lshl_b32 s4, s31, 10
	s_add_i32 s4, s20, s4
	s_waitcnt lgkmcnt(0)
	v_add_f32_e32 v130, v130, v131
	v_lshl_add_u32 v131, v230, 4, s4
	ds_write_b32 v131, v130 offset:2560
.LBB0_830:
	s_or_b64 exec, exec, s[0:1]
	v_mul_f32_e32 v130, v15, v15
	s_waitcnt lgkmcnt(0)
	v_mul_f32_e32 v131, v17, v17
	v_fmac_f32_e32 v130, v14, v14
	v_fmac_f32_e32 v131, v16, v16
	v_add_f32_e32 v130, v130, v131
	v_mul_f32_e32 v131, v11, v11
	v_mul_f32_e32 v132, v13, v13
	v_fmac_f32_e32 v131, v10, v10
	v_fmac_f32_e32 v132, v12, v12
	v_add_f32_e32 v131, v131, v132
	v_add_f32_e32 v130, v131, v130
	v_mul_f32_e32 v131, v7, v7
	v_mul_f32_e32 v132, v9, v9
	v_fmac_f32_e32 v131, v6, v6
	v_fmac_f32_e32 v132, v8, v8
	v_add_f32_e32 v131, v131, v132
	v_add_f32_e32 v130, v131, v130
	v_mul_f32_e32 v131, v3, v3
	v_mul_f32_e32 v132, v5, v5
	v_fmac_f32_e32 v131, v2, v2
	v_fmac_f32_e32 v132, v4, v4
	v_add_f32_e32 v131, v131, v132
	v_add_f32_e32 v130, v131, v130
	v_mov_b32_e32 v131, v130
	s_nop 1
	v_permlane16_swap_b32_e32 v130, v131
	v_add_f32_e32 v130, v130, v131
	v_mov_b32_e32 v131, v130
	s_nop 1
	v_permlane32_swap_b32_e32 v130, v131
	s_and_saveexec_b64 s[0:1], s[38:39]
	s_cbranch_execz .LBB0_832
	s_lshl_b32 s4, s31, 10
	s_add_i32 s4, s20, s4
	s_waitcnt lgkmcnt(0)
	v_add_f32_e32 v130, v130, v131
	v_lshl_add_u32 v131, v230, 4, s4
	ds_write_b32 v131, v130 offset:2816

;     __device__ __forceinline__ void publish(const f32x4 (&v)[2][2][4][2], const Unit& u, int wr, int wc, int fr, int fq, PG8_LAS unsigned char* lds, int wid, int lane) const {
;     ...
;                 float s = 0.f;
; #pragma unroll
;                 for (int bj = 0; bj < 2; ++bj)
; #pragma unroll
;                     for (int n = 0; n < 2; ++n) { const f32x4 x = v[ai][bj][m][n]; s += (x[0] * x[0] + x[1] * x[1]) + (x[2] * x[2] + x[3] * x[3]); }
;                 s += __shfl_xor(s, 16); s += __shfl_xor(s, 32);
;                 if (fq == 0) P[(ai * HALF + wr * 64 + m * 16 + fr) * 4 + wc] = s;
.LBB0_930:
	v_mul_f32_e32 v130, v99, v99
	v_mul_f32_e32 v131, v101, v101
	v_fmac_f32_e32 v130, v98, v98
	v_fmac_f32_e32 v131, v100, v100
	v_add_f32_e32 v130, v130, v131
	v_mul_f32_e32 v131, v103, v103
	v_mul_f32_e32 v132, v105, v105
	v_fmac_f32_e32 v131, v102, v102
	v_fmac_f32_e32 v132, v104, v104
	v_add_f32_e32 v131, v131, v132
	v_add_f32_e32 v130, v130, v131
	v_mul_f32_e32 v131, v107, v107
	v_mul_f32_e32 v132, v109, v109
	v_fmac_f32_e32 v131, v106, v106
	v_fmac_f32_e32 v132, v108, v108
	v_add_f32_e32 v131, v131, v132
	v_add_f32_e32 v130, v131, v130
	v_mul_f32_e32 v131, v111, v111
	v_mul_f32_e32 v132, v113, v113
	v_fmac_f32_e32 v131, v110, v110
	v_fmac_f32_e32 v132, v112, v112
	v_add_f32_e32 v131, v131, v132
	v_add_f32_e32 v130, v131, v130
	v_mov_b32_e32 v131, v130
	s_nop 1
	v_permlane16_swap_b32_e32 v130, v131
	v_add_f32_e32 v130, v130, v131
	v_mov_b32_e32 v131, v130
	s_nop 1
	v_permlane32_swap_b32_e32 v130, v131
	s_and_saveexec_b64 s[4:5], s[38:39]
	s_cbranch_execz .LBB0_932
	s_lshl_b32 s6, s31, 10
	s_add_i32 s6, s20, s6
	v_lshl_add_u32 v132, v230, 4, s6
	s_waitcnt lgkmcnt(0)
	v_add_f32_e32 v130, v130, v131
	ds_write_b32 v132, v130
.LBB0_932:
	s_or_b64 exec, exec, s[4:5]
	v_mul_f32_e32 v130, v127, v127
	s_waitcnt lgkmcnt(0)
	v_mul_f32_e32 v131, v129, v129
	v_fmac_f32_e32 v130, v126, v126
	v_fmac_f32_e32 v131, v128, v128
	v_add_f32_e32 v130, v130, v131
	v_mul_f32_e32 v131, v123, v123
	v_mul_f32_e32 v132, v125, v125
	v_fmac_f32_e32 v131, v122, v122
	v_fmac_f32_e32 v132, v124, v124
	v_add_f32_e32 v131, v131, v132
	v_add_f32_e32 v130, v130, v131
	v_mul_f32_e32 v131, v115, v115
	v_mul_f32_e32 v132, v117, v117
	v_fmac_f32_e32 v131, v114, v114
	v_fmac_f32_e32 v132, v116, v116
	v_add_f32_e32 v131, v131, v132
	v_add_f32_e32 v130, v131, v130
	v_mul_f32_e32 v131, v119, v119
	v_mul_f32_e32 v132, v121, v121
	v_fmac_f32_e32 v131, v118, v118
	v_fmac_f32_e32 v132, v120, v120
	v_add_f32_e32 v131, v131, v132
	v_add_f32_e32 v130, v131, v130
	v_mov_b32_e32 v131, v130
	s_nop 1
	v_permlane16_swap_b32_e32 v130, v131
	v_add_f32_e32 v130, v130, v131
	v_mov_b32_e32 v131, v130
	s_nop 1
	v_permlane32_swap_b32_e32 v130, v131
	s_and_saveexec_b64 s[4:5], s[38:39]
	s_cbranch_execz .LBB0_934
	s_lshl_b32 s6, s31, 10
	s_add_i32 s6, s20, s6
	v_lshl_add_u32 v132, v230, 4, s6
	s_waitcnt lgkmcnt(0)
	v_add_f32_e32 v130, v130, v131
	ds_write_b32 v132, v130 offset:256
.LBB0_934:
	s_or_b64 exec, exec, s[4:5]
	v_mul_f32_e32 v130, v95, v95
	s_waitcnt lgkmcnt(0)
	v_mul_f32_e32 v131, v97, v97
	v_fmac_f32_e32 v130, v94, v94
	v_fmac_f32_e32 v131, v96, v96
	v_add_f32_e32 v130, v130, v131
	v_mul_f32_e32 v131, v91, v91
	v_mul_f32_e32 v132, v93, v93
	v_fmac_f32_e32 v131, v90, v90
	v_fmac_f32_e32 v132, v92, v92
	v_add_f32_e32 v131, v131, v132
	v_add_f32_e32 v130, v130, v131
	v_mul_f32_e32 v131, v87, v87
	v_mul_f32_e32 v132, v89, v89
	v_fmac_f32_e32 v131, v86, v86
	v_fmac_f32_e32 v132, v88, v88
	v_add_f32_e32 v131, v131, v132
	v_add_f32_e32 v130, v131, v130
	v_mul_f32_e32 v131, v83, v83
	v_mul_f32_e32 v132, v85, v85
	v_fmac_f32_e32 v131, v82, v82
	v_fmac_f32_e32 v132, v84, v84
	v_add_f32_e32 v131, v131, v132
	v_add_f32_e32 v130, v131, v130
	v_mov_b32_e32 v131, v130
	s_nop 1
	v_permlane16_swap_b32_e32 v130, v131
	v_add_f32_e32 v130, v130, v131
	v_mov_b32_e32 v131, v130
	s_nop 1
	v_permlane32_swap_b32_e32 v130, v131
	s_and_saveexec_b64 s[4:5], s[38:39]
	s_cbranch_execz .LBB0_936
	s_lshl_b32 s6, s31, 10
	s_add_i32 s6, s20, s6
	v_lshl_add_u32 v132, v230, 4, s6
	s_waitcnt lgkmcnt(0)
	v_add_f32_e32 v130, v130, v131
	ds_write_b32 v132, v130 offset:512
.LBB0_936:
	s_or_b64 exec, exec, s[4:5]
	v_mul_f32_e32 v130, v79, v79
	s_waitcnt lgkmcnt(0)
	v_mul_f32_e32 v131, v81, v81
	v_fmac_f32_e32 v130, v78, v78
	v_fmac_f32_e32 v131, v80, v80
	v_add_f32_e32 v130, v130, v131
	v_mul_f32_e32 v131, v75, v75
	v_mul_f32_e32 v132, v77, v77
	v_fmac_f32_e32 v131, v74, v74
	v_fmac_f32_e32 v132, v76, v76
	v_add_f32_e32 v131, v131, v132
	v_add_f32_e32 v130, v130, v131
	v_mul_f32_e32 v131, v71, v71
	v_mul_f32_e32 v132, v73, v73
	v_fmac_f32_e32 v131, v70, v70
	v_fmac_f32_e32 v132, v72, v72
	v_add_f32_e32 v131, v131, v132
	v_add_f32_e32 v130, v131, v130
	v_mul_f32_e32 v131, v67, v67
	v_mul_f32_e32 v132, v69, v69
	v_fmac_f32_e32 v131, v66, v66
	v_fmac_f32_e32 v132, v68, v68
	v_add_f32_e32 v131, v131, v132
	v_add_f32_e32 v130, v131, v130
	v_mov_b32_e32 v131, v130
	s_nop 1
	v_permlane16_swap_b32_e32 v130, v131
	v_add_f32_e32 v130, v130, v131
	v_mov_b32_e32 v131, v130
	s_nop 1
	v_permlane32_swap_b32_e32 v130, v131
	s_and_saveexec_b64 s[4:5], s[38:39]
	s_cbranch_execz .LBB0_938
	s_lshl_b32 s6, s31, 10
	s_add_i32 s6, s20, s6
	v_lshl_add_u32 v132, v230, 4, s6
	s_waitcnt lgkmcnt(0)
	v_add_f32_e32 v130, v130, v131
	ds_write_b32 v132, v130 offset:768
;     __device__ __forceinline__ void publish(const f32x4 (&v)[2][2][4][2], const Unit& u, int wr, int wc, int fr, int fq, PG8_LAS unsigned char* lds, int wid, int lane) const {
;     ...
;                 float s = 0.f;
; #pragma unroll
;                 for (int bj = 0; bj < 2; ++bj)
; #pragma unroll
;                     for (int n = 0; n < 2; ++n) { const f32x4 x = v[ai][bj][m][n]; s += (x[0] * x[0] + x[1] * x[1]) + (x[2] * x[2] + x[3] * x[3]); }
;                 s += __shfl_xor(s, 16); s += __shfl_xor(s, 32);
;                 if (fq == 0) P[(ai * HALF + wr * 64 + m * 16 + fr) * 4 + wc] = s;
.LBB0_938:
	s_or_b64 exec, exec, s[4:5]
	v_mul_f32_e32 v130, v63, v63
	s_waitcnt lgkmcnt(0)
	v_mul_f32_e32 v131, v65, v65
	v_fmac_f32_e32 v130, v62, v62
	v_fmac_f32_e32 v131, v64, v64
	v_add_f32_e32 v130, v130, v131
	v_mul_f32_e32 v131, v59, v59
	v_mul_f32_e32 v132, v61, v61
	v_fmac_f32_e32 v131, v58, v58
	v_fmac_f32_e32 v132, v60, v60
	v_add_f32_e32 v131, v131, v132
	v_add_f32_e32 v130, v130, v131
	v_mul_f32_e32 v131, v55, v55
	v_mul_f32_e32 v132, v57, v57
	v_fmac_f32_e32 v131, v54, v54
	v_fmac_f32_e32 v132, v56, v56
	v_add_f32_e32 v131, v131, v132
	v_add_f32_e32 v130, v131, v130
	v_mul_f32_e32 v131, v51, v51
	v_mul_f32_e32 v132, v53, v53
	v_fmac_f32_e32 v131, v50, v50
	v_fmac_f32_e32 v132, v52, v52
	v_add_f32_e32 v131, v131, v132
	v_add_f32_e32 v130, v131, v130
	v_mov_b32_e32 v131, v130
	s_nop 1
	v_permlane16_swap_b32_e32 v130, v131
	v_add_f32_e32 v130, v130, v131
	v_mov_b32_e32 v131, v130
	s_nop 1
	v_permlane32_swap_b32_e32 v130, v131
	s_and_saveexec_b64 s[4:5], s[38:39]
	s_cbranch_execz .LBB0_940
	s_lshl_b32 s6, s31, 10
	s_add_i32 s6, s20, s6
	v_lshl_add_u32 v132, v230, 4, s6
	s_waitcnt lgkmcnt(0)
	v_add_f32_e32 v130, v130, v131
	ds_write_b32 v132, v130 offset:2048
.LBB0_940:
	s_or_b64 exec, exec, s[4:5]
	v_mul_f32_e32 v130, v47, v47
	s_waitcnt lgkmcnt(0)
	v_mul_f32_e32 v131, v49, v49
	v_fmac_f32_e32 v130, v46, v46
	v_fmac_f32_e32 v131, v48, v48
	v_add_f32_e32 v130, v130, v131
	v_mul_f32_e32 v131, v43, v43
	v_mul_f32_e32 v132, v45, v45
	v_fmac_f32_e32 v131, v42, v42
	v_fmac_f32_e32 v132, v44, v44
	v_add_f32_e32 v131, v131, v132
	v_add_f32_e32 v130, v130, v131
	v_mul_f32_e32 v131, v39, v39
	v_mul_f32_e32 v132, v41, v41
	v_fmac_f32_e32 v131, v38, v38
	v_fmac_f32_e32 v132, v40, v40
	v_add_f32_e32 v131, v131, v132
	v_add_f32_e32 v130, v131, v130
	v_mul_f32_e32 v131, v35, v35
	v_mul_f32_e32 v132, v37, v37
	v_fmac_f32_e32 v131, v34, v34
	v_fmac_f32_e32 v132, v36, v36
	v_add_f32_e32 v131, v131, v132
	v_add_f32_e32 v130, v131, v130
	v_mov_b32_e32 v131, v130
	s_nop 1
	v_permlane16_swap_b32_e32 v130, v131
	v_add_f32_e32 v130, v130, v131
	v_mov_b32_e32 v131, v130
	s_nop 1
	v_permlane32_swap_b32_e32 v130, v131
	s_and_saveexec_b64 s[4:5], s[38:39]
	s_cbranch_execz .LBB0_942
	s_lshl_b32 s6, s31, 10
	s_add_i32 s6, s20, s6
	v_lshl_add_u32 v132, v230, 4, s6
	s_waitcnt lgkmcnt(0)
	v_add_f32_e32 v130, v130, v131
	ds_write_b32 v132, v130 offset:2304
.LBB0_942:
	s_or_b64 exec, exec, s[4:5]
	v_mul_f32_e32 v130, v31, v31
	s_waitcnt lgkmcnt(0)
	v_mul_f32_e32 v131, v33, v33
	v_fmac_f32_e32 v130, v30, v30
	v_fmac_f32_e32 v131, v32, v32
	v_add_f32_e32 v130, v130, v131
	v_mul_f32_e32 v131, v27, v27
	v_mul_f32_e32 v132, v29, v29
	v_fmac_f32_e32 v131, v26, v26
	v_fmac_f32_e32 v132, v28, v28
	v_add_f32_e32 v131, v131, v132
	v_add_f32_e32 v130, v130, v131
	v_mul_f32_e32 v131, v23, v23
	v_mul_f32_e32 v132, v25, v25
	v_fmac_f32_e32 v131, v22, v22
	v_fmac_f32_e32 v132, v24, v24
	v_add_f32_e32 v131, v131, v132
	v_add_f32_e32 v130, v131, v130
	v_mul_f32_e32 v131, v19, v19
	v_mul_f32_e32 v132, v21, v21
	v_fmac_f32_e32 v131, v18, v18
	v_fmac_f32_e32 v132, v20, v20
	v_add_f32_e32 v131, v131, v132
	v_add_f32_e32 v130, v131, v130
	v_mov_b32_e32 v131, v130
	s_nop 1
	v_permlane16_swap_b32_e32 v130, v131
	v_add_f32_e32 v130, v130, v131
	v_mov_b32_e32 v131, v130
	s_nop 1
	v_permlane32_swap_b32_e32 v130, v131
	s_and_saveexec_b64 s[4:5], s[38:39]
	s_cbranch_execz .LBB0_944
	s_lshl_b32 s6, s31, 10
	s_add_i32 s6, s20, s6
	v_lshl_add_u32 v132, v230, 4, s6
	s_waitcnt lgkmcnt(0)
	v_add_f32_e32 v130, v130, v131
	ds_write_b32 v132, v130 offset:2560
.LBB0_944:
	s_or_b64 exec, exec, s[4:5]
	v_mul_f32_e32 v130, v15, v15
	s_waitcnt lgkmcnt(0)
	v_mul_f32_e32 v131, v17, v17
	v_fmac_f32_e32 v130, v14, v14
	v_fmac_f32_e32 v131, v16, v16
	v_add_f32_e32 v130, v130, v131
	v_mul_f32_e32 v131, v11, v11
	v_mul_f32_e32 v132, v13, v13
	v_fmac_f32_e32 v131, v10, v10
	v_fmac_f32_e32 v132, v12, v12
	v_add_f32_e32 v131, v131, v132
	v_add_f32_e32 v130, v130, v131
	v_mul_f32_e32 v131, v7, v7
	v_mul_f32_e32 v132, v9, v9
	v_fmac_f32_e32 v131, v6, v6
	v_fmac_f32_e32 v132, v8, v8
	v_add_f32_e32 v131, v131, v132
	v_add_f32_e32 v130, v131, v130
	v_mul_f32_e32 v131, v3, v3
	v_mul_f32_e32 v132, v5, v5
	v_fmac_f32_e32 v131, v2, v2
	v_fmac_f32_e32 v132, v4, v4
	v_add_f32_e32 v131, v131, v132
	v_add_f32_e32 v130, v131, v130
	v_mov_b32_e32 v131, v130
	s_nop 1
	v_permlane16_swap_b32_e32 v130, v131
	v_add_f32_e32 v130, v130, v131
	v_mov_b32_e32 v131, v130
	s_nop 1
	v_permlane32_swap_b32_e32 v130, v131
	s_and_saveexec_b64 s[4:5], s[38:39]
	s_cbranch_execz .LBB0_946
	s_lshl_b32 s6, s31, 10
	s_add_i32 s20, s20, s6
	v_lshl_add_u32 v132, v230, 4, s20
	s_waitcnt lgkmcnt(0)
	v_add_f32_e32 v130, v130, v131
	ds_write_b32 v132, v130 offset:2816

;     __device__ __forceinline__ void publish(const f32x4 (&v)[2][2][4][2], const Unit& u, int wr, int wc, int fr, int fq, PG8_LAS unsigned char* lds, int wid, int lane) const {
;     ...
;                 float s = 0.f;
; #pragma unroll
;                 for (int bj = 0; bj < 2; ++bj)
; #pragma unroll
;                     for (int n = 0; n < 2; ++n) { const f32x4 x = v[ai][bj][m][n]; s += (x[0] * x[0] + x[1] * x[1]) + (x[2] * x[2] + x[3] * x[3]); }
;                 s += __shfl_xor(s, 16); s += __shfl_xor(s, 32);
;                 if (fq == 0) P[(ai * HALF + wr * 64 + m * 16 + fr) * 4 + wc] = s;
.LBB0_1806:
	s_or_b64 exec, exec, s[6:7]
	v_mul_f32_e32 v130, v111, v111
	s_waitcnt lgkmcnt(0)
	v_mul_f32_e32 v131, v113, v113
	v_fmac_f32_e32 v130, v110, v110
	v_fmac_f32_e32 v131, v112, v112
	v_add_f32_e32 v130, v130, v131
	v_mul_f32_e32 v131, v107, v107
	v_mul_f32_e32 v132, v109, v109
	v_fmac_f32_e32 v131, v106, v106
	v_fmac_f32_e32 v132, v108, v108
	v_add_f32_e32 v131, v131, v132
	v_add_f32_e32 v130, v131, v130
	v_mul_f32_e32 v131, v103, v103
	v_mul_f32_e32 v132, v105, v105
	v_fmac_f32_e32 v131, v102, v102
	v_fmac_f32_e32 v132, v104, v104
	v_add_f32_e32 v131, v131, v132
	v_add_f32_e32 v130, v131, v130
	v_mul_f32_e32 v131, v99, v99
	v_mul_f32_e32 v132, v101, v101
	v_fmac_f32_e32 v131, v98, v98
	v_fmac_f32_e32 v132, v100, v100
	v_add_f32_e32 v131, v131, v132
	v_add_f32_e32 v130, v131, v130
	v_mov_b32_e32 v131, v130
	s_nop 1
	v_permlane16_swap_b32_e32 v130, v131
	v_add_f32_e32 v130, v130, v131
	v_mov_b32_e32 v131, v130
	s_nop 1
	v_permlane32_swap_b32_e32 v130, v131
	s_and_saveexec_b64 s[6:7], s[38:39]
	s_movk_i32 s25, 0x1600
	s_movk_i32 s24, 0x410
	s_cbranch_execz .LBB0_1808
	s_lshl_b32 s5, s46, 10
	s_add_i32 s5, s1, s5
	s_waitcnt lgkmcnt(0)
	v_add_f32_e32 v130, v130, v131
	v_lshl_add_u32 v131, v187, 4, s5
	ds_write_b32 v131, v130 offset:256
.LBB0_1808:
	s_or_b64 exec, exec, s[6:7]
	v_mul_f32_e32 v130, v95, v95
	s_waitcnt lgkmcnt(0)
	v_mul_f32_e32 v131, v97, v97
	v_fmac_f32_e32 v130, v94, v94
	v_fmac_f32_e32 v131, v96, v96
	v_add_f32_e32 v130, v130, v131
	v_mul_f32_e32 v131, v91, v91
	v_mul_f32_e32 v132, v93, v93
	v_fmac_f32_e32 v131, v90, v90
	v_fmac_f32_e32 v132, v92, v92
	v_add_f32_e32 v131, v131, v132
	v_add_f32_e32 v130, v131, v130
	v_mul_f32_e32 v131, v87, v87
	v_mul_f32_e32 v132, v89, v89
	v_fmac_f32_e32 v131, v86, v86
	v_fmac_f32_e32 v132, v88, v88
	v_add_f32_e32 v131, v131, v132
	v_add_f32_e32 v130, v131, v130
	v_mul_f32_e32 v131, v83, v83
	v_mul_f32_e32 v132, v85, v85
	v_fmac_f32_e32 v131, v82, v82
	v_fmac_f32_e32 v132, v84, v84
	v_add_f32_e32 v131, v131, v132
	v_add_f32_e32 v130, v131, v130
	v_mov_b32_e32 v131, v130
	s_nop 1
	v_permlane16_swap_b32_e32 v130, v131
	v_add_f32_e32 v130, v130, v131
	v_mov_b32_e32 v131, v130
	s_nop 1
	v_permlane32_swap_b32_e32 v130, v131
	s_and_saveexec_b64 s[6:7], s[38:39]
	s_cbranch_execz .LBB0_1810
	s_lshl_b32 s5, s46, 10
	s_add_i32 s5, s1, s5
	s_waitcnt lgkmcnt(0)
	v_add_f32_e32 v130, v130, v131
	v_lshl_add_u32 v131, v187, 4, s5
	ds_write_b32 v131, v130 offset:512
.LBB0_1810:
	s_or_b64 exec, exec, s[6:7]
	v_mul_f32_e32 v130, v79, v79
	s_waitcnt lgkmcnt(0)
	v_mul_f32_e32 v131, v81, v81
	v_fmac_f32_e32 v130, v78, v78
	v_fmac_f32_e32 v131, v80, v80
	v_add_f32_e32 v130, v130, v131
	v_mul_f32_e32 v131, v75, v75
	v_mul_f32_e32 v132, v77, v77
	v_fmac_f32_e32 v131, v74, v74
	v_fmac_f32_e32 v132, v76, v76
	v_add_f32_e32 v131, v131, v132
	v_add_f32_e32 v130, v131, v130
	v_mul_f32_e32 v131, v71, v71
	v_mul_f32_e32 v132, v73, v73
	v_fmac_f32_e32 v131, v70, v70
	v_fmac_f32_e32 v132, v72, v72
	v_add_f32_e32 v131, v131, v132
	v_add_f32_e32 v130, v131, v130
	v_mul_f32_e32 v131, v67, v67
	v_mul_f32_e32 v132, v69, v69
	v_fmac_f32_e32 v131, v66, v66
	v_fmac_f32_e32 v132, v68, v68
	v_add_f32_e32 v131, v131, v132
	v_add_f32_e32 v130, v131, v130
	v_mov_b32_e32 v131, v130
	s_nop 1
	v_permlane16_swap_b32_e32 v130, v131
	v_add_f32_e32 v130, v130, v131
	v_mov_b32_e32 v131, v130
	s_nop 1
	v_permlane32_swap_b32_e32 v130, v131
	s_and_saveexec_b64 s[6:7], s[38:39]
	s_cbranch_execz .LBB0_1812
	s_lshl_b32 s5, s46, 10
	s_add_i32 s5, s1, s5
	s_waitcnt lgkmcnt(0)
	v_add_f32_e32 v130, v130, v131
	v_lshl_add_u32 v131, v187, 4, s5
	ds_write_b32 v131, v130 offset:768
;     __device__ __forceinline__ void publish(const f32x4 (&v)[2][2][4][2], const Unit& u, int wr, int wc, int fr, int fq, PG8_LAS unsigned char* lds, int wid, int lane) const {
;     ...
;                 float s = 0.f;
; #pragma unroll
;                 for (int bj = 0; bj < 2; ++bj)
; #pragma unroll
;                     for (int n = 0; n < 2; ++n) { const f32x4 x = v[ai][bj][m][n]; s += (x[0] * x[0] + x[1] * x[1]) + (x[2] * x[2] + x[3] * x[3]); }
;                 s += __shfl_xor(s, 16); s += __shfl_xor(s, 32);
;                 if (fq == 0) P[(ai * HALF + wr * 64 + m * 16 + fr) * 4 + wc] = s;
.LBB0_1812:
	s_or_b64 exec, exec, s[6:7]
	v_mul_f32_e32 v130, v63, v63
	s_waitcnt lgkmcnt(0)
	v_mul_f32_e32 v131, v65, v65
	v_fmac_f32_e32 v130, v62, v62
	v_fmac_f32_e32 v131, v64, v64
	v_add_f32_e32 v130, v130, v131
	v_mul_f32_e32 v131, v59, v59
	v_mul_f32_e32 v132, v61, v61
	v_fmac_f32_e32 v131, v58, v58
	v_fmac_f32_e32 v132, v60, v60
	v_add_f32_e32 v131, v131, v132
	v_add_f32_e32 v130, v131, v130
	v_mul_f32_e32 v131, v55, v55
	v_mul_f32_e32 v132, v57, v57
	v_fmac_f32_e32 v131, v54, v54
	v_fmac_f32_e32 v132, v56, v56
	v_add_f32_e32 v131, v131, v132
	v_add_f32_e32 v130, v131, v130
	v_mul_f32_e32 v131, v51, v51
	v_mul_f32_e32 v132, v53, v53
	v_fmac_f32_e32 v131, v50, v50
	v_fmac_f32_e32 v132, v52, v52
	v_add_f32_e32 v131, v131, v132
	v_add_f32_e32 v130, v131, v130
	v_mov_b32_e32 v131, v130
	s_nop 1
	v_permlane16_swap_b32_e32 v130, v131
	v_add_f32_e32 v130, v130, v131
	v_mov_b32_e32 v131, v130
	s_nop 1
	v_permlane32_swap_b32_e32 v130, v131
	s_and_saveexec_b64 s[6:7], s[38:39]
	s_cbranch_execz .LBB0_1814
	s_lshl_b32 s5, s46, 10
	s_add_i32 s5, s1, s5
	s_waitcnt lgkmcnt(0)
	v_add_f32_e32 v130, v130, v131
	v_lshl_add_u32 v131, v187, 4, s5
	ds_write_b32 v131, v130 offset:2048
.LBB0_1814:
	s_or_b64 exec, exec, s[6:7]
	v_mul_f32_e32 v130, v47, v47
	s_waitcnt lgkmcnt(0)
	v_mul_f32_e32 v131, v49, v49
	v_fmac_f32_e32 v130, v46, v46
	v_fmac_f32_e32 v131, v48, v48
	v_add_f32_e32 v130, v130, v131
	v_mul_f32_e32 v131, v43, v43
	v_mul_f32_e32 v132, v45, v45
	v_fmac_f32_e32 v131, v42, v42
	v_fmac_f32_e32 v132, v44, v44
	v_add_f32_e32 v131, v131, v132
	v_add_f32_e32 v130, v131, v130
	v_mul_f32_e32 v131, v39, v39
	v_mul_f32_e32 v132, v41, v41
	v_fmac_f32_e32 v131, v38, v38
	v_fmac_f32_e32 v132, v40, v40
	v_add_f32_e32 v131, v131, v132
	v_add_f32_e32 v130, v131, v130
	v_mul_f32_e32 v131, v35, v35
	v_mul_f32_e32 v132, v37, v37
	v_fmac_f32_e32 v131, v34, v34
	v_fmac_f32_e32 v132, v36, v36
	v_add_f32_e32 v131, v131, v132
	v_add_f32_e32 v130, v131, v130
	v_mov_b32_e32 v131, v130
	s_nop 1
	v_permlane16_swap_b32_e32 v130, v131
	v_add_f32_e32 v130, v130, v131
	v_mov_b32_e32 v131, v130
	s_nop 1
	v_permlane32_swap_b32_e32 v130, v131
	s_and_saveexec_b64 s[6:7], s[38:39]
	s_cbranch_execz .LBB0_1816
	s_lshl_b32 s5, s46, 10
	s_add_i32 s5, s1, s5
	s_waitcnt lgkmcnt(0)
	v_add_f32_e32 v130, v130, v131
	v_lshl_add_u32 v131, v187, 4, s5
	ds_write_b32 v131, v130 offset:2304
.LBB0_1816:
	s_or_b64 exec, exec, s[6:7]
	v_mul_f32_e32 v130, v31, v31
	s_waitcnt lgkmcnt(0)
	v_mul_f32_e32 v131, v33, v33
	v_fmac_f32_e32 v130, v30, v30
	v_fmac_f32_e32 v131, v32, v32
	v_add_f32_e32 v130, v130, v131
	v_mul_f32_e32 v131, v27, v27
	v_mul_f32_e32 v132, v29, v29
	v_fmac_f32_e32 v131, v26, v26
	v_fmac_f32_e32 v132, v28, v28
	v_add_f32_e32 v131, v131, v132
	v_add_f32_e32 v130, v131, v130
	v_mul_f32_e32 v131, v23, v23
	v_mul_f32_e32 v132, v25, v25
	v_fmac_f32_e32 v131, v22, v22
	v_fmac_f32_e32 v132, v24, v24
	v_add_f32_e32 v131, v131, v132
	v_add_f32_e32 v130, v131, v130
	v_mul_f32_e32 v131, v19, v19
	v_mul_f32_e32 v132, v21, v21
	v_fmac_f32_e32 v131, v18, v18
	v_fmac_f32_e32 v132, v20, v20
	v_add_f32_e32 v131, v131, v132
	v_add_f32_e32 v130, v131, v130
	v_mov_b32_e32 v131, v130
	s_nop 1
	v_permlane16_swap_b32_e32 v130, v131
	v_add_f32_e32 v130, v130, v131
	v_mov_b32_e32 v131, v130
	s_nop 1
	v_permlane32_swap_b32_e32 v130, v131
	s_and_saveexec_b64 s[6:7], s[38:39]
	s_cbranch_execz .LBB0_1818
	s_lshl_b32 s5, s46, 10
	s_add_i32 s5, s1, s5
	s_waitcnt lgkmcnt(0)
	v_add_f32_e32 v130, v130, v131
	v_lshl_add_u32 v131, v187, 4, s5
	ds_write_b32 v131, v130 offset:2560
.LBB0_1818:
	s_or_b64 exec, exec, s[6:7]
	v_mul_f32_e32 v130, v15, v15
	s_waitcnt lgkmcnt(0)
	v_mul_f32_e32 v131, v17, v17
	v_fmac_f32_e32 v130, v14, v14
	v_fmac_f32_e32 v131, v16, v16
	v_add_f32_e32 v130, v130, v131
	v_mul_f32_e32 v131, v11, v11
	v_mul_f32_e32 v132, v13, v13
	v_fmac_f32_e32 v131, v10, v10
	v_fmac_f32_e32 v132, v12, v12
	v_add_f32_e32 v131, v131, v132
	v_add_f32_e32 v130, v131, v130
	v_mul_f32_e32 v131, v7, v7
	v_mul_f32_e32 v132, v9, v9
	v_fmac_f32_e32 v131, v6, v6
	v_fmac_f32_e32 v132, v8, v8
	v_add_f32_e32 v131, v131, v132
	v_add_f32_e32 v130, v131, v130
	v_mul_f32_e32 v131, v3, v3
	v_mul_f32_e32 v132, v5, v5
	v_fmac_f32_e32 v131, v2, v2
	v_fmac_f32_e32 v132, v4, v4
	v_add_f32_e32 v131, v131, v132
	v_add_f32_e32 v130, v131, v130
	v_mov_b32_e32 v131, v130
	s_nop 1
	v_permlane16_swap_b32_e32 v130, v131
	v_add_f32_e32 v130, v130, v131
	v_mov_b32_e32 v131, v130
	s_nop 1
	v_permlane32_swap_b32_e32 v130, v131
	s_and_saveexec_b64 s[6:7], s[38:39]
	s_cbranch_execz .LBB0_1820
	s_lshl_b32 s5, s46, 10
	s_add_i32 s5, s1, s5
	s_waitcnt lgkmcnt(0)
	v_add_f32_e32 v130, v130, v131
	v_lshl_add_u32 v131, v187, 4, s5
	ds_write_b32 v131, v130 offset:2816

;     __device__ __forceinline__ void publish(const f32x4 (&v)[2][2][4][2], const Unit& u, int wr, int wc, int fr, int fq, PG8_LAS unsigned char* lds, int wid, int lane) const {
;     ...
;                 float s = 0.f;
; #pragma unroll
;                 for (int bj = 0; bj < 2; ++bj)
; #pragma unroll
;                     for (int n = 0; n < 2; ++n) { const f32x4 x = v[ai][bj][m][n]; s += (x[0] * x[0] + x[1] * x[1]) + (x[2] * x[2] + x[3] * x[3]); }
;                 s += __shfl_xor(s, 16); s += __shfl_xor(s, 32);
;                 if (fq == 0) P[(ai * HALF + wr * 64 + m * 16 + fr) * 4 + wc] = s;
.LBB0_1846:
	s_or_b64 exec, exec, s[8:9]
	v_mul_f32_e32 v130, v111, v111
	s_waitcnt lgkmcnt(0)
	v_mul_f32_e32 v131, v113, v113
	v_fmac_f32_e32 v130, v110, v110
	v_fmac_f32_e32 v131, v112, v112
	v_add_f32_e32 v130, v130, v131
	v_mul_f32_e32 v131, v107, v107
	v_mul_f32_e32 v132, v109, v109
	v_fmac_f32_e32 v131, v106, v106
	v_fmac_f32_e32 v132, v108, v108
	v_add_f32_e32 v131, v131, v132
	v_add_f32_e32 v130, v130, v131
	v_mul_f32_e32 v131, v103, v103
	v_mul_f32_e32 v132, v105, v105
	v_fmac_f32_e32 v131, v102, v102
	v_fmac_f32_e32 v132, v104, v104
	v_add_f32_e32 v131, v131, v132
	v_add_f32_e32 v130, v131, v130
	v_mul_f32_e32 v131, v99, v99
	v_mul_f32_e32 v132, v101, v101
	v_fmac_f32_e32 v131, v98, v98
	v_fmac_f32_e32 v132, v100, v100
	v_add_f32_e32 v131, v131, v132
	v_add_f32_e32 v130, v131, v130
	v_mov_b32_e32 v131, v130
	s_nop 1
	v_permlane16_swap_b32_e32 v130, v131
	v_add_f32_e32 v130, v130, v131
	v_mov_b32_e32 v131, v130
	s_nop 1
	v_permlane32_swap_b32_e32 v130, v131
	s_and_saveexec_b64 s[8:9], s[38:39]
	s_cbranch_execz .LBB0_1848
	s_lshl_b32 s10, s46, 10
	s_add_i32 s10, s1, s10
	v_lshl_add_u32 v132, v187, 4, s10
	s_waitcnt lgkmcnt(0)
	v_add_f32_e32 v130, v130, v131
	ds_write_b32 v132, v130 offset:256
.LBB0_1848:
	s_or_b64 exec, exec, s[8:9]
	v_mul_f32_e32 v130, v95, v95
	s_waitcnt lgkmcnt(0)
	v_mul_f32_e32 v131, v97, v97
	v_fmac_f32_e32 v130, v94, v94
	v_fmac_f32_e32 v131, v96, v96
	v_add_f32_e32 v130, v130, v131
	v_mul_f32_e32 v131, v91, v91
	v_mul_f32_e32 v132, v93, v93
	v_fmac_f32_e32 v131, v90, v90
	v_fmac_f32_e32 v132, v92, v92
	v_add_f32_e32 v131, v131, v132
	v_add_f32_e32 v130, v130, v131
	v_mul_f32_e32 v131, v87, v87
	v_mul_f32_e32 v132, v89, v89
	v_fmac_f32_e32 v131, v86, v86
	v_fmac_f32_e32 v132, v88, v88
	v_add_f32_e32 v131, v131, v132
	v_add_f32_e32 v130, v131, v130
	v_mul_f32_e32 v131, v83, v83
	v_mul_f32_e32 v132, v85, v85
	v_fmac_f32_e32 v131, v82, v82
	v_fmac_f32_e32 v132, v84, v84
	v_add_f32_e32 v131, v131, v132
	v_add_f32_e32 v130, v131, v130
	v_mov_b32_e32 v131, v130
	s_nop 1
	v_permlane16_swap_b32_e32 v130, v131
	v_add_f32_e32 v130, v130, v131
	v_mov_b32_e32 v131, v130
	s_nop 1
	v_permlane32_swap_b32_e32 v130, v131
	s_and_saveexec_b64 s[8:9], s[38:39]
	s_cbranch_execz .LBB0_1850
	s_lshl_b32 s10, s46, 10
	s_add_i32 s10, s1, s10
	v_lshl_add_u32 v132, v187, 4, s10
	s_waitcnt lgkmcnt(0)
	v_add_f32_e32 v130, v130, v131
	ds_write_b32 v132, v130 offset:512
.LBB0_1850:
	s_or_b64 exec, exec, s[8:9]
	v_mul_f32_e32 v130, v79, v79
	s_waitcnt lgkmcnt(0)
	v_mul_f32_e32 v131, v81, v81
	v_fmac_f32_e32 v130, v78, v78
	v_fmac_f32_e32 v131, v80, v80
	v_add_f32_e32 v130, v130, v131
	v_mul_f32_e32 v131, v75, v75
	v_mul_f32_e32 v132, v77, v77
	v_fmac_f32_e32 v131, v74, v74
	v_fmac_f32_e32 v132, v76, v76
	v_add_f32_e32 v131, v131, v132
	v_add_f32_e32 v130, v130, v131
	v_mul_f32_e32 v131, v71, v71
	v_mul_f32_e32 v132, v73, v73
	v_fmac_f32_e32 v131, v70, v70
	v_fmac_f32_e32 v132, v72, v72
	v_add_f32_e32 v131, v131, v132
	v_add_f32_e32 v130, v131, v130
	v_mul_f32_e32 v131, v67, v67
	v_mul_f32_e32 v132, v69, v69
	v_fmac_f32_e32 v131, v66, v66
	v_fmac_f32_e32 v132, v68, v68
	v_add_f32_e32 v131, v131, v132
	v_add_f32_e32 v130, v131, v130
	v_mov_b32_e32 v131, v130
	s_nop 1
	v_permlane16_swap_b32_e32 v130, v131
	v_add_f32_e32 v130, v130, v131
	v_mov_b32_e32 v131, v130
	s_nop 1
	v_permlane32_swap_b32_e32 v130, v131
	s_and_saveexec_b64 s[8:9], s[38:39]
	s_cbranch_execz .LBB0_1852
	s_lshl_b32 s10, s46, 10
	s_add_i32 s10, s1, s10
	v_lshl_add_u32 v132, v187, 4, s10
	s_waitcnt lgkmcnt(0)
	v_add_f32_e32 v130, v130, v131
	ds_write_b32 v132, v130 offset:768
;     __device__ __forceinline__ void publish(const f32x4 (&v)[2][2][4][2], const Unit& u, int wr, int wc, int fr, int fq, PG8_LAS unsigned char* lds, int wid, int lane) const {
;     ...
;                 float s = 0.f;
; #pragma unroll
;                 for (int bj = 0; bj < 2; ++bj)
; #pragma unroll
;                     for (int n = 0; n < 2; ++n) { const f32x4 x = v[ai][bj][m][n]; s += (x[0] * x[0] + x[1] * x[1]) + (x[2] * x[2] + x[3] * x[3]); }
;                 s += __shfl_xor(s, 16); s += __shfl_xor(s, 32);
;                 if (fq == 0) P[(ai * HALF + wr * 64 + m * 16 + fr) * 4 + wc] = s;
.LBB0_1852:
	s_or_b64 exec, exec, s[8:9]
	v_mul_f32_e32 v130, v63, v63
	s_waitcnt lgkmcnt(0)
	v_mul_f32_e32 v131, v65, v65
	v_fmac_f32_e32 v130, v62, v62
	v_fmac_f32_e32 v131, v64, v64
	v_add_f32_e32 v130, v130, v131
	v_mul_f32_e32 v131, v59, v59
	v_mul_f32_e32 v132, v61, v61
	v_fmac_f32_e32 v131, v58, v58
	v_fmac_f32_e32 v132, v60, v60
	v_add_f32_e32 v131, v131, v132
	v_add_f32_e32 v130, v130, v131
	v_mul_f32_e32 v131, v55, v55
	v_mul_f32_e32 v132, v57, v57
	v_fmac_f32_e32 v131, v54, v54
	v_fmac_f32_e32 v132, v56, v56
	v_add_f32_e32 v131, v131, v132
	v_add_f32_e32 v130, v131, v130
	v_mul_f32_e32 v131, v51, v51
	v_mul_f32_e32 v132, v53, v53
	v_fmac_f32_e32 v131, v50, v50
	v_fmac_f32_e32 v132, v52, v52
	v_add_f32_e32 v131, v131, v132
	v_add_f32_e32 v130, v131, v130
	v_mov_b32_e32 v131, v130
	s_nop 1
	v_permlane16_swap_b32_e32 v130, v131
	v_add_f32_e32 v130, v130, v131
	v_mov_b32_e32 v131, v130
	s_nop 1
	v_permlane32_swap_b32_e32 v130, v131
	s_and_saveexec_b64 s[8:9], s[38:39]
	s_cbranch_execz .LBB0_1854
	s_lshl_b32 s10, s46, 10
	s_add_i32 s10, s1, s10
	v_lshl_add_u32 v132, v187, 4, s10
	s_waitcnt lgkmcnt(0)
	v_add_f32_e32 v130, v130, v131
	ds_write_b32 v132, v130 offset:2048
.LBB0_1854:
	s_or_b64 exec, exec, s[8:9]
	v_mul_f32_e32 v130, v47, v47
	s_waitcnt lgkmcnt(0)
	v_mul_f32_e32 v131, v49, v49
	v_fmac_f32_e32 v130, v46, v46
	v_fmac_f32_e32 v131, v48, v48
	v_add_f32_e32 v130, v130, v131
	v_mul_f32_e32 v131, v43, v43
	v_mul_f32_e32 v132, v45, v45
	v_fmac_f32_e32 v131, v42, v42
	v_fmac_f32_e32 v132, v44, v44
	v_add_f32_e32 v131, v131, v132
	v_add_f32_e32 v130, v130, v131
	v_mul_f32_e32 v131, v39, v39
	v_mul_f32_e32 v132, v41, v41
	v_fmac_f32_e32 v131, v38, v38
	v_fmac_f32_e32 v132, v40, v40
	v_add_f32_e32 v131, v131, v132
	v_add_f32_e32 v130, v131, v130
	v_mul_f32_e32 v131, v35, v35
	v_mul_f32_e32 v132, v37, v37
	v_fmac_f32_e32 v131, v34, v34
	v_fmac_f32_e32 v132, v36, v36
	v_add_f32_e32 v131, v131, v132
	v_add_f32_e32 v130, v131, v130
	v_mov_b32_e32 v131, v130
	s_nop 1
	v_permlane16_swap_b32_e32 v130, v131
	v_add_f32_e32 v130, v130, v131
	v_mov_b32_e32 v131, v130
	s_nop 1
	v_permlane32_swap_b32_e32 v130, v131
	s_and_saveexec_b64 s[8:9], s[38:39]
	s_cbranch_execz .LBB0_1856
	s_lshl_b32 s10, s46, 10
	s_add_i32 s10, s1, s10
	v_lshl_add_u32 v132, v187, 4, s10
	s_waitcnt lgkmcnt(0)
	v_add_f32_e32 v130, v130, v131
	ds_write_b32 v132, v130 offset:2304
.LBB0_1856:
	s_or_b64 exec, exec, s[8:9]
	v_mul_f32_e32 v130, v31, v31
	s_waitcnt lgkmcnt(0)
	v_mul_f32_e32 v131, v33, v33
	v_fmac_f32_e32 v130, v30, v30
	v_fmac_f32_e32 v131, v32, v32
	v_add_f32_e32 v130, v130, v131
	v_mul_f32_e32 v131, v27, v27
	v_mul_f32_e32 v132, v29, v29
	v_fmac_f32_e32 v131, v26, v26
	v_fmac_f32_e32 v132, v28, v28
	v_add_f32_e32 v131, v131, v132
	v_add_f32_e32 v130, v130, v131
	v_mul_f32_e32 v131, v23, v23
	v_mul_f32_e32 v132, v25, v25
	v_fmac_f32_e32 v131, v22, v22
	v_fmac_f32_e32 v132, v24, v24
	v_add_f32_e32 v131, v131, v132
	v_add_f32_e32 v130, v131, v130
	v_mul_f32_e32 v131, v19, v19
	v_mul_f32_e32 v132, v21, v21
	v_fmac_f32_e32 v131, v18, v18
	v_fmac_f32_e32 v132, v20, v20
	v_add_f32_e32 v131, v131, v132
	v_add_f32_e32 v130, v131, v130
	v_mov_b32_e32 v131, v130
	s_nop 1
	v_permlane16_swap_b32_e32 v130, v131
	v_add_f32_e32 v130, v130, v131
	v_mov_b32_e32 v131, v130
	s_nop 1
	v_permlane32_swap_b32_e32 v130, v131
	s_and_saveexec_b64 s[8:9], s[38:39]
	s_cbranch_execz .LBB0_1858
	s_lshl_b32 s10, s46, 10
	s_add_i32 s10, s1, s10
	v_lshl_add_u32 v132, v187, 4, s10
	s_waitcnt lgkmcnt(0)
	v_add_f32_e32 v130, v130, v131
	ds_write_b32 v132, v130 offset:2560
.LBB0_1858:
	s_or_b64 exec, exec, s[8:9]
	v_mul_f32_e32 v130, v15, v15
	s_waitcnt lgkmcnt(0)
	v_mul_f32_e32 v131, v17, v17
	v_fmac_f32_e32 v130, v14, v14
	v_fmac_f32_e32 v131, v16, v16
	v_add_f32_e32 v130, v130, v131
	v_mul_f32_e32 v131, v11, v11
	v_mul_f32_e32 v132, v13, v13
	v_fmac_f32_e32 v131, v10, v10
	v_fmac_f32_e32 v132, v12, v12
	v_add_f32_e32 v131, v131, v132
	v_add_f32_e32 v130, v130, v131
	v_mul_f32_e32 v131, v7, v7
	v_mul_f32_e32 v132, v9, v9
	v_fmac_f32_e32 v131, v6, v6
	v_fmac_f32_e32 v132, v8, v8
	v_add_f32_e32 v131, v131, v132
	v_add_f32_e32 v130, v131, v130
	v_mul_f32_e32 v131, v3, v3
	v_mul_f32_e32 v132, v5, v5
	v_fmac_f32_e32 v131, v2, v2
	v_fmac_f32_e32 v132, v4, v4
	v_add_f32_e32 v131, v131, v132
	v_add_f32_e32 v130, v131, v130
	v_mov_b32_e32 v131, v130
	s_nop 1
	v_permlane16_swap_b32_e32 v130, v131
	v_add_f32_e32 v130, v130, v131
	v_mov_b32_e32 v131, v130
	s_nop 1
	v_permlane32_swap_b32_e32 v130, v131
	s_and_saveexec_b64 s[8:9], s[38:39]
	s_cbranch_execz .LBB0_1860
	s_lshl_b32 s10, s46, 10
	s_add_i32 s1, s1, s10
	v_lshl_add_u32 v132, v187, 4, s1
	s_waitcnt lgkmcnt(0)
	v_add_f32_e32 v130, v130, v131
	ds_write_b32 v132, v130 offset:2816

;     __device__ __forceinline__ void publish(const f32x4 (&v)[2][2][4][2], const Unit& u, int wr, int wc, int fr, int fq, PG8_LAS unsigned char* lds, int wid, int lane) const {
;     ...
;                 float s = 0.f;
; #pragma unroll
;                 for (int bj = 0; bj < 2; ++bj)
; #pragma unroll
;                     for (int n = 0; n < 2; ++n) { const f32x4 x = v[ai][bj][m][n]; s += (x[0] * x[0] + x[1] * x[1]) + (x[2] * x[2] + x[3] * x[3]); }
;                 s += __shfl_xor(s, 16); s += __shfl_xor(s, 32);
;                 if (fq == 0) P[(ai * HALF + wr * 64 + m * 16 + fr) * 4 + wc] = s;
.LBB0_2337:
	s_or_b64 exec, exec, s[0:1]
	v_mul_f32_e32 v130, v111, v111
	s_waitcnt lgkmcnt(0)
	v_mul_f32_e32 v131, v113, v113
	v_fmac_f32_e32 v130, v110, v110
	v_fmac_f32_e32 v131, v112, v112
	v_add_f32_e32 v130, v130, v131
	v_mul_f32_e32 v131, v107, v107
	v_mul_f32_e32 v132, v109, v109
	v_fmac_f32_e32 v131, v106, v106
	v_fmac_f32_e32 v132, v108, v108
	v_add_f32_e32 v131, v131, v132
	v_add_f32_e32 v130, v131, v130
	v_mul_f32_e32 v131, v103, v103
	v_mul_f32_e32 v132, v105, v105
	v_fmac_f32_e32 v131, v102, v102
	v_fmac_f32_e32 v132, v104, v104
	v_add_f32_e32 v131, v131, v132
	v_add_f32_e32 v130, v131, v130
	v_mul_f32_e32 v131, v99, v99
	v_mul_f32_e32 v132, v101, v101
	v_fmac_f32_e32 v131, v98, v98
	v_fmac_f32_e32 v132, v100, v100
	v_add_f32_e32 v131, v131, v132
	v_add_f32_e32 v130, v131, v130
	v_mov_b32_e32 v131, v130
	s_nop 1
	v_permlane16_swap_b32_e32 v130, v131
	v_add_f32_e32 v130, v130, v131
	v_mov_b32_e32 v131, v130
	s_nop 1
	v_permlane32_swap_b32_e32 v130, v131
	s_and_saveexec_b64 s[0:1], s[40:41]
	s_movk_i32 s25, 0x1600
	s_movk_i32 s24, 0x410
	s_cbranch_execz .LBB0_2339
	s_lshl_b32 s4, s49, 10
	s_add_i32 s4, s21, s4
	s_waitcnt lgkmcnt(0)
	v_add_f32_e32 v130, v130, v131
	v_lshl_add_u32 v131, v185, 4, s4
	ds_write_b32 v131, v130 offset:256
.LBB0_2339:
	s_or_b64 exec, exec, s[0:1]
	v_mul_f32_e32 v130, v95, v95
	s_waitcnt lgkmcnt(0)
	v_mul_f32_e32 v131, v97, v97
	v_fmac_f32_e32 v130, v94, v94
	v_fmac_f32_e32 v131, v96, v96
	v_add_f32_e32 v130, v130, v131
	v_mul_f32_e32 v131, v91, v91
	v_mul_f32_e32 v132, v93, v93
	v_fmac_f32_e32 v131, v90, v90
	v_fmac_f32_e32 v132, v92, v92
	v_add_f32_e32 v131, v131, v132
	v_add_f32_e32 v130, v131, v130
	v_mul_f32_e32 v131, v87, v87
	v_mul_f32_e32 v132, v89, v89
	v_fmac_f32_e32 v131, v86, v86
	v_fmac_f32_e32 v132, v88, v88
	v_add_f32_e32 v131, v131, v132
	v_add_f32_e32 v130, v131, v130
	v_mul_f32_e32 v131, v83, v83
	v_mul_f32_e32 v132, v85, v85
	v_fmac_f32_e32 v131, v82, v82
	v_fmac_f32_e32 v132, v84, v84
	v_add_f32_e32 v131, v131, v132
	v_add_f32_e32 v130, v131, v130
	v_mov_b32_e32 v131, v130
	s_nop 1
	v_permlane16_swap_b32_e32 v130, v131
	v_add_f32_e32 v130, v130, v131
	v_mov_b32_e32 v131, v130
	s_nop 1
	v_permlane32_swap_b32_e32 v130, v131
	s_and_saveexec_b64 s[0:1], s[40:41]
	s_cbranch_execz .LBB0_2341
	s_lshl_b32 s4, s49, 10
	s_add_i32 s4, s21, s4
	s_waitcnt lgkmcnt(0)
	v_add_f32_e32 v130, v130, v131
	v_lshl_add_u32 v131, v185, 4, s4
	ds_write_b32 v131, v130 offset:512
.LBB0_2341:
	s_or_b64 exec, exec, s[0:1]
	v_mul_f32_e32 v130, v79, v79
	s_waitcnt lgkmcnt(0)
	v_mul_f32_e32 v131, v81, v81
	v_fmac_f32_e32 v130, v78, v78
	v_fmac_f32_e32 v131, v80, v80
	v_add_f32_e32 v130, v130, v131
	v_mul_f32_e32 v131, v75, v75
	v_mul_f32_e32 v132, v77, v77
	v_fmac_f32_e32 v131, v74, v74
	v_fmac_f32_e32 v132, v76, v76
	v_add_f32_e32 v131, v131, v132
	v_add_f32_e32 v130, v131, v130
	v_mul_f32_e32 v131, v71, v71
	v_mul_f32_e32 v132, v73, v73
	v_fmac_f32_e32 v131, v70, v70
	v_fmac_f32_e32 v132, v72, v72
	v_add_f32_e32 v131, v131, v132
	v_add_f32_e32 v130, v131, v130
	v_mul_f32_e32 v131, v67, v67
	v_mul_f32_e32 v132, v69, v69
	v_fmac_f32_e32 v131, v66, v66
	v_fmac_f32_e32 v132, v68, v68
	v_add_f32_e32 v131, v131, v132
	v_add_f32_e32 v130, v131, v130
	v_mov_b32_e32 v131, v130
	s_nop 1
	v_permlane16_swap_b32_e32 v130, v131
	v_add_f32_e32 v130, v130, v131
	v_mov_b32_e32 v131, v130
	s_nop 1
	v_permlane32_swap_b32_e32 v130, v131
	s_and_saveexec_b64 s[0:1], s[40:41]
	s_cbranch_execz .LBB0_2343
	s_lshl_b32 s4, s49, 10
	s_add_i32 s4, s21, s4
	s_waitcnt lgkmcnt(0)
	v_add_f32_e32 v130, v130, v131
	v_lshl_add_u32 v131, v185, 4, s4
	ds_write_b32 v131, v130 offset:768
;     __device__ __forceinline__ void publish(const f32x4 (&v)[2][2][4][2], const Unit& u, int wr, int wc, int fr, int fq, PG8_LAS unsigned char* lds, int wid, int lane) const {
;     ...
;                 float s = 0.f;
; #pragma unroll
;                 for (int bj = 0; bj < 2; ++bj)
; #pragma unroll
;                     for (int n = 0; n < 2; ++n) { const f32x4 x = v[ai][bj][m][n]; s += (x[0] * x[0] + x[1] * x[1]) + (x[2] * x[2] + x[3] * x[3]); }
;                 s += __shfl_xor(s, 16); s += __shfl_xor(s, 32);
;                 if (fq == 0) P[(ai * HALF + wr * 64 + m * 16 + fr) * 4 + wc] = s;
.LBB0_2343:
	s_or_b64 exec, exec, s[0:1]
	v_mul_f32_e32 v130, v63, v63
	s_waitcnt lgkmcnt(0)
	v_mul_f32_e32 v131, v65, v65
	v_fmac_f32_e32 v130, v62, v62
	v_fmac_f32_e32 v131, v64, v64
	v_add_f32_e32 v130, v130, v131
	v_mul_f32_e32 v131, v59, v59
	v_mul_f32_e32 v132, v61, v61
	v_fmac_f32_e32 v131, v58, v58
	v_fmac_f32_e32 v132, v60, v60
	v_add_f32_e32 v131, v131, v132
	v_add_f32_e32 v130, v131, v130
	v_mul_f32_e32 v131, v55, v55
	v_mul_f32_e32 v132, v57, v57
	v_fmac_f32_e32 v131, v54, v54
	v_fmac_f32_e32 v132, v56, v56
	v_add_f32_e32 v131, v131, v132
	v_add_f32_e32 v130, v131, v130
	v_mul_f32_e32 v131, v51, v51
	v_mul_f32_e32 v132, v53, v53
	v_fmac_f32_e32 v131, v50, v50
	v_fmac_f32_e32 v132, v52, v52
	v_add_f32_e32 v131, v131, v132
	v_add_f32_e32 v130, v131, v130
	v_mov_b32_e32 v131, v130
	s_nop 1
	v_permlane16_swap_b32_e32 v130, v131
	v_add_f32_e32 v130, v130, v131
	v_mov_b32_e32 v131, v130
	s_nop 1
	v_permlane32_swap_b32_e32 v130, v131
	s_and_saveexec_b64 s[0:1], s[40:41]
	s_cbranch_execz .LBB0_2345
	s_lshl_b32 s4, s49, 10
	s_add_i32 s4, s21, s4
	s_waitcnt lgkmcnt(0)
	v_add_f32_e32 v130, v130, v131
	v_lshl_add_u32 v131, v185, 4, s4
	ds_write_b32 v131, v130 offset:2048
.LBB0_2345:
	s_or_b64 exec, exec, s[0:1]
	v_mul_f32_e32 v130, v47, v47
	s_waitcnt lgkmcnt(0)
	v_mul_f32_e32 v131, v49, v49
	v_fmac_f32_e32 v130, v46, v46
	v_fmac_f32_e32 v131, v48, v48
	v_add_f32_e32 v130, v130, v131
	v_mul_f32_e32 v131, v43, v43
	v_mul_f32_e32 v132, v45, v45
	v_fmac_f32_e32 v131, v42, v42
	v_fmac_f32_e32 v132, v44, v44
	v_add_f32_e32 v131, v131, v132
	v_add_f32_e32 v130, v131, v130
	v_mul_f32_e32 v131, v39, v39
	v_mul_f32_e32 v132, v41, v41
	v_fmac_f32_e32 v131, v38, v38
	v_fmac_f32_e32 v132, v40, v40
	v_add_f32_e32 v131, v131, v132
	v_add_f32_e32 v130, v131, v130
	v_mul_f32_e32 v131, v35, v35
	v_mul_f32_e32 v132, v37, v37
	v_fmac_f32_e32 v131, v34, v34
	v_fmac_f32_e32 v132, v36, v36
	v_add_f32_e32 v131, v131, v132
	v_add_f32_e32 v130, v131, v130
	v_mov_b32_e32 v131, v130
	s_nop 1
	v_permlane16_swap_b32_e32 v130, v131
	v_add_f32_e32 v130, v130, v131
	v_mov_b32_e32 v131, v130
	s_nop 1
	v_permlane32_swap_b32_e32 v130, v131
	s_and_saveexec_b64 s[0:1], s[40:41]
	s_cbranch_execz .LBB0_2347
	s_lshl_b32 s4, s49, 10
	s_add_i32 s4, s21, s4
	s_waitcnt lgkmcnt(0)
	v_add_f32_e32 v130, v130, v131
	v_lshl_add_u32 v131, v185, 4, s4
	ds_write_b32 v131, v130 offset:2304
.LBB0_2347:
	s_or_b64 exec, exec, s[0:1]
	v_mul_f32_e32 v130, v31, v31
	s_waitcnt lgkmcnt(0)
	v_mul_f32_e32 v131, v33, v33
	v_fmac_f32_e32 v130, v30, v30
	v_fmac_f32_e32 v131, v32, v32
	v_add_f32_e32 v130, v130, v131
	v_mul_f32_e32 v131, v27, v27
	v_mul_f32_e32 v132, v29, v29
	v_fmac_f32_e32 v131, v26, v26
	v_fmac_f32_e32 v132, v28, v28
	v_add_f32_e32 v131, v131, v132
	v_add_f32_e32 v130, v131, v130
	v_mul_f32_e32 v131, v23, v23
	v_mul_f32_e32 v132, v25, v25
	v_fmac_f32_e32 v131, v22, v22
	v_fmac_f32_e32 v132, v24, v24
	v_add_f32_e32 v131, v131, v132
	v_add_f32_e32 v130, v131, v130
	v_mul_f32_e32 v131, v19, v19
	v_mul_f32_e32 v132, v21, v21
	v_fmac_f32_e32 v131, v18, v18
	v_fmac_f32_e32 v132, v20, v20
	v_add_f32_e32 v131, v131, v132
	v_add_f32_e32 v130, v131, v130
	v_mov_b32_e32 v131, v130
	s_nop 1
	v_permlane16_swap_b32_e32 v130, v131
	v_add_f32_e32 v130, v130, v131
	v_mov_b32_e32 v131, v130
	s_nop 1
	v_permlane32_swap_b32_e32 v130, v131
	s_and_saveexec_b64 s[0:1], s[40:41]
	s_cbranch_execz .LBB0_2349
	s_lshl_b32 s4, s49, 10
	s_add_i32 s4, s21, s4
	s_waitcnt lgkmcnt(0)
	v_add_f32_e32 v130, v130, v131
	v_lshl_add_u32 v131, v185, 4, s4
	ds_write_b32 v131, v130 offset:2560
.LBB0_2349:
	s_or_b64 exec, exec, s[0:1]
	v_mul_f32_e32 v130, v15, v15
	s_waitcnt lgkmcnt(0)
	v_mul_f32_e32 v131, v17, v17
	v_fmac_f32_e32 v130, v14, v14
	v_fmac_f32_e32 v131, v16, v16
	v_add_f32_e32 v130, v130, v131
	v_mul_f32_e32 v131, v11, v11
	v_mul_f32_e32 v132, v13, v13
	v_fmac_f32_e32 v131, v10, v10
	v_fmac_f32_e32 v132, v12, v12
	v_add_f32_e32 v131, v131, v132
	v_add_f32_e32 v130, v131, v130
	v_mul_f32_e32 v131, v7, v7
	v_mul_f32_e32 v132, v9, v9
	v_fmac_f32_e32 v131, v6, v6
	v_fmac_f32_e32 v132, v8, v8
	v_add_f32_e32 v131, v131, v132
	v_add_f32_e32 v130, v131, v130
	v_mul_f32_e32 v131, v3, v3
	v_mul_f32_e32 v132, v5, v5
	v_fmac_f32_e32 v131, v2, v2
	v_fmac_f32_e32 v132, v4, v4
	v_add_f32_e32 v131, v131, v132
	v_add_f32_e32 v130, v131, v130
	v_mov_b32_e32 v131, v130
	s_nop 1
	v_permlane16_swap_b32_e32 v130, v131
	v_add_f32_e32 v130, v130, v131
	v_mov_b32_e32 v131, v130
	s_nop 1
	v_permlane32_swap_b32_e32 v130, v131
	s_and_saveexec_b64 s[0:1], s[40:41]
	s_cbranch_execz .LBB0_2351
	s_lshl_b32 s4, s49, 10
	s_add_i32 s4, s21, s4
	s_waitcnt lgkmcnt(0)
	v_add_f32_e32 v130, v130, v131
	v_lshl_add_u32 v131, v185, 4, s4
	ds_write_b32 v131, v130 offset:2816

;     __device__ __forceinline__ void fused(f32x4 (&acc)[2][2][4][2], const Unit& u, int wr, int wc, int fr, int fq, PG8_LAS unsigned char* lds, int wid, int lane) const {
;     ...
;         const int col0 = u.pn * BM + wc * 32 + 8 * fq;
;         const float* cb = comb + (u.pm < 16 ? 0 : 3 * 2048) + col0;
;     ...
;             for (int bj = 0; bj < 2; ++bj) { vg[bj][0] = *(const f32x4*)(cb + bj * HALF); vg[bj][1] = *(const f32x4*)(cb + bj * HALF + 4); }
; #pragma unroll
;             for (int ai = 0; ai < 2; ++ai) {
;                 if (ai == 1 && !xin) {
;                     asm volatile("" ::: "memory");
; #pragma unroll
;                     for (int m = 0; m < 4; ++m)
; #pragma unroll
;                         for (int bj = 0; bj < 2; ++bj) xp[m][bj] = NT_FX ? __builtin_nontemporal_load((const u32x4*)(X + (size_t)(u.pm * BM + HALF + wr * 64 + m * 16 + fr) * 2048 + col0 + bj * HALF)) : *(const u32x4*)(X + (size_t)(u.pm * BM + HALF + wr * 64 + m * 16 + fr) * 2048 + col0 + bj * HALF);
;                 }
; #pragma unroll
;                 for (int m = 0; m < 4; ++m) { const int r = ai * HALF + wr * 64 + m * 16 + fr; const float rs = S[r]; const size_t off = (size_t)(u.pm * BM + r) * 2048 + col0;
; #pragma unroll
;                     for (int bj = 0; bj < 2; ++bj) { f32x4 x0, x1;
;                         if (xin) { x0 = *(const f32x4*)(xin + off + bj * HALF); x1 = *(const f32x4*)(xin + off + bj * HALF + 4); }
;                         else { const u32x4 w = xp[m][bj];
;                             x0 = (f32x4){__builtin_bit_cast(float, w.x << 16), __builtin_bit_cast(float, w.x & 0xffff0000u), __builtin_bit_cast(float, w.y << 16), __builtin_bit_cast(float, w.y & 0xffff0000u)};
;                             x1 = (f32x4){__builtin_bit_cast(float, w.z << 16), __builtin_bit_cast(float, w.z & 0xffff0000u), __builtin_bit_cast(float, w.w << 16), __builtin_bit_cast(float, w.w & 0xffff0000u)}; }
;                         acc[ai][bj][m][0] = x0 + vg[bj][0] * (acc[ai][bj][m][0] * rs); acc[ai][bj][m][1] = x1 + vg[bj][1] * (acc[ai][bj][m][1] * rs); }
.LBB0_2375:
	s_or_b64 exec, exec, s[6:7]
	s_mul_i32 s4, s22, 0x12000
	v_readlane_b32 s5, v252, 40
	s_add_u32 s4, s5, s4
	v_readlane_b32 s5, v252, 41
	s_addc_u32 s5, s5, 0
	s_cmp_lt_i32 s48, 16
	s_cselect_b32 s6, 0, 0x6000
	s_add_u32 s4, s4, s6
	s_addc_u32 s5, s5, 0
	v_lshl_add_u64 v[182:183], v[180:181], 2, s[4:5]
	s_waitcnt lgkmcnt(0)
	s_barrier
	global_load_dwordx4 v[138:141], v[182:183], off offset:16
	global_load_dwordx4 v[142:145], v[182:183], off
	global_load_dwordx4 v[130:133], v[182:183], off offset:528
	global_load_dwordx4 v[134:137], v[182:183], off offset:512
	v_lshl_add_u32 v186, v184, 2, 0
	ds_read_b32 v192, v186 offset:4096
	s_waitcnt vmcnt(0)
	v_lshlrev_b32_e32 v200, 16, v174
	v_and_b32_e32 v201, 0xffff0000, v174
	v_lshlrev_b32_e32 v174, 16, v175
	v_and_b32_e32 v175, 0xffff0000, v175
	v_lshlrev_b32_e32 v202, 16, v176
	v_and_b32_e32 v203, 0xffff0000, v176
	v_lshlrev_b32_e32 v176, 16, v177
	v_and_b32_e32 v177, 0xffff0000, v177
	s_waitcnt lgkmcnt(0)
	v_pk_mul_f32 v[128:129], v[128:129], v[192:193] op_sel_hi:[1,0]
	v_pk_mul_f32 v[124:125], v[124:125], v[192:193] op_sel_hi:[1,0]
	v_pk_mul_f32 v[126:127], v[126:127], v[192:193] op_sel_hi:[1,0]
	v_pk_mul_f32 v[122:123], v[122:123], v[192:193] op_sel_hi:[1,0]
	v_pk_mul_f32 v[120:121], v[120:121], v[192:193] op_sel_hi:[1,0]
	v_pk_mul_f32 v[118:119], v[118:119], v[192:193] op_sel_hi:[1,0]
	v_pk_mul_f32 v[116:117], v[116:117], v[192:193] op_sel_hi:[1,0]
	v_pk_mul_f32 v[114:115], v[114:115], v[192:193] op_sel_hi:[1,0]
	s_andn2_b64 vcc, exec, s[12:13]
	v_pk_fma_f32 v[124:125], v[140:141], v[124:125], v[176:177]
	v_pk_fma_f32 v[128:129], v[144:145], v[128:129], v[174:175]
	v_lshlrev_b32_e32 v174, 16, v170
	v_and_b32_e32 v175, 0xffff0000, v170
	v_lshlrev_b32_e32 v170, 16, v171
	v_and_b32_e32 v171, 0xffff0000, v171
	v_lshlrev_b32_e32 v176, 16, v172
	v_and_b32_e32 v177, 0xffff0000, v172
	v_lshlrev_b32_e32 v172, 16, v173
	v_and_b32_e32 v173, 0xffff0000, v173
	v_pk_fma_f32 v[126:127], v[142:143], v[126:127], v[200:201]
	v_pk_fma_f32 v[122:123], v[138:139], v[122:123], v[202:203]
	v_pk_fma_f32 v[118:119], v[134:135], v[118:119], v[174:175]
	v_pk_fma_f32 v[120:121], v[136:137], v[120:121], v[170:171]
	v_pk_fma_f32 v[114:115], v[130:131], v[114:115], v[176:177]
	v_pk_fma_f32 v[116:117], v[132:133], v[116:117], v[172:173]
	v_lshlrev_b32_e32 v172, 16, v166
	ds_read_b32 v170, v186 offset:4160
	v_and_b32_e32 v173, 0xffff0000, v166
	v_lshlrev_b32_e32 v166, 16, v167
	v_and_b32_e32 v167, 0xffff0000, v167
	v_lshlrev_b32_e32 v174, 16, v168
	v_and_b32_e32 v175, 0xffff0000, v168
	v_lshlrev_b32_e32 v168, 16, v169
	v_and_b32_e32 v169, 0xffff0000, v169
	s_waitcnt lgkmcnt(0)
	v_pk_mul_f32 v[112:113], v[112:113], v[170:171] op_sel_hi:[1,0]
	v_pk_mul_f32 v[108:109], v[108:109], v[170:171] op_sel_hi:[1,0]
	v_pk_mul_f32 v[110:111], v[110:111], v[170:171] op_sel_hi:[1,0]
	v_pk_fma_f32 v[112:113], v[144:145], v[112:113], v[166:167]
	v_pk_mul_f32 v[106:107], v[106:107], v[170:171] op_sel_hi:[1,0]
	v_pk_fma_f32 v[108:109], v[140:141], v[108:109], v[168:169]
	v_lshlrev_b32_e32 v166, 16, v162
	v_and_b32_e32 v167, 0xffff0000, v162
	v_lshlrev_b32_e32 v162, 16, v163
	v_and_b32_e32 v163, 0xffff0000, v163
	v_lshlrev_b32_e32 v168, 16, v164
	v_and_b32_e32 v169, 0xffff0000, v164
	v_lshlrev_b32_e32 v164, 16, v165
	v_and_b32_e32 v165, 0xffff0000, v165
	v_pk_mul_f32 v[104:105], v[104:105], v[170:171] op_sel_hi:[1,0]
	v_pk_mul_f32 v[102:103], v[102:103], v[170:171] op_sel_hi:[1,0]
	v_pk_mul_f32 v[100:101], v[100:101], v[170:171] op_sel_hi:[1,0]
	v_pk_mul_f32 v[98:99], v[98:99], v[170:171] op_sel_hi:[1,0]
	v_pk_fma_f32 v[110:111], v[142:143], v[110:111], v[172:173]
	v_pk_fma_f32 v[106:107], v[138:139], v[106:107], v[174:175]
	v_pk_fma_f32 v[102:103], v[134:135], v[102:103], v[166:167]
	v_pk_fma_f32 v[104:105], v[136:137], v[104:105], v[162:163]
	v_pk_fma_f32 v[98:99], v[130:131], v[98:99], v[168:169]
	v_pk_fma_f32 v[100:101], v[132:133], v[100:101], v[164:165]
	v_lshlrev_b32_e32 v164, 16, v158
	ds_read_b32 v162, v186 offset:4224
	v_and_b32_e32 v165, 0xffff0000, v158
	v_lshlrev_b32_e32 v158, 16, v159
	v_and_b32_e32 v159, 0xffff0000, v159
	v_lshlrev_b32_e32 v166, 16, v160
	v_and_b32_e32 v167, 0xffff0000, v160
	v_lshlrev_b32_e32 v160, 16, v161
	v_and_b32_e32 v161, 0xffff0000, v161
	s_waitcnt lgkmcnt(0)
	v_pk_mul_f32 v[96:97], v[96:97], v[162:163] op_sel_hi:[1,0]
	v_pk_mul_f32 v[92:93], v[92:93], v[162:163] op_sel_hi:[1,0]
	v_pk_mul_f32 v[94:95], v[94:95], v[162:163] op_sel_hi:[1,0]
	v_pk_fma_f32 v[96:97], v[144:145], v[96:97], v[158:159]
	v_pk_mul_f32 v[90:91], v[90:91], v[162:163] op_sel_hi:[1,0]
	v_pk_fma_f32 v[92:93], v[140:141], v[92:93], v[160:161]
	v_lshlrev_b32_e32 v158, 16, v154
	v_and_b32_e32 v159, 0xffff0000, v154
	v_lshlrev_b32_e32 v154, 16, v155
	v_and_b32_e32 v155, 0xffff0000, v155
	v_lshlrev_b32_e32 v160, 16, v156
	v_and_b32_e32 v161, 0xffff0000, v156
	v_lshlrev_b32_e32 v156, 16, v157
	v_and_b32_e32 v157, 0xffff0000, v157
	v_pk_mul_f32 v[88:89], v[88:89], v[162:163] op_sel_hi:[1,0]
	v_pk_mul_f32 v[86:87], v[86:87], v[162:163] op_sel_hi:[1,0]
	v_pk_mul_f32 v[84:85], v[84:85], v[162:163] op_sel_hi:[1,0]
	v_pk_mul_f32 v[82:83], v[82:83], v[162:163] op_sel_hi:[1,0]
	v_pk_fma_f32 v[94:95], v[142:143], v[94:95], v[164:165]
	v_pk_fma_f32 v[90:91], v[138:139], v[90:91], v[166:167]
	v_pk_fma_f32 v[86:87], v[134:135], v[86:87], v[158:159]
	v_pk_fma_f32 v[88:89], v[136:137], v[88:89], v[154:155]
	v_pk_fma_f32 v[82:83], v[130:131], v[82:83], v[160:161]
	v_pk_fma_f32 v[84:85], v[132:133], v[84:85], v[156:157]
	v_lshlrev_b32_e32 v158, 16, v152
	ds_read_b32 v154, v186 offset:4288
	v_and_b32_e32 v159, 0xffff0000, v152
	v_lshlrev_b32_e32 v152, 16, v153
	v_and_b32_e32 v153, 0xffff0000, v153
	v_lshlrev_b32_e32 v156, 16, v150
	s_waitcnt lgkmcnt(0)
;     __device__ __forceinline__ void fused(f32x4 (&acc)[2][2][4][2], const Unit& u, int wr, int wc, int fr, int fq, PG8_LAS unsigned char* lds, int wid, int lane) const {
;     ...
;             for (int ai = 0; ai < 2; ++ai) {
;                 if (ai == 1 && !xin) {
;                     asm volatile("" ::: "memory");
; #pragma unroll
;                     for (int m = 0; m < 4; ++m)
; #pragma unroll
;                         for (int bj = 0; bj < 2; ++bj) xp[m][bj] = NT_FX ? __builtin_nontemporal_load((const u32x4*)(X + (size_t)(u.pm * BM + HALF + wr * 64 + m * 16 + fr) * 2048 + col0 + bj * HALF)) : *(const u32x4*)(X + (size_t)(u.pm * BM + HALF + wr * 64 + m * 16 + fr) * 2048 + col0 + bj * HALF);
;                 }
; #pragma unroll
;                 for (int m = 0; m < 4; ++m) { const int r = ai * HALF + wr * 64 + m * 16 + fr; const float rs = S[r]; const size_t off = (size_t)(u.pm * BM + r) * 2048 + col0;
; #pragma unroll
;                     for (int bj = 0; bj < 2; ++bj) { f32x4 x0, x1;
;                         if (xin) { x0 = *(const f32x4*)(xin + off + bj * HALF); x1 = *(const f32x4*)(xin + off + bj * HALF + 4); }
;                         else { const u32x4 w = xp[m][bj];
;                             x0 = (f32x4){__builtin_bit_cast(float, w.x << 16), __builtin_bit_cast(float, w.x & 0xffff0000u), __builtin_bit_cast(float, w.y << 16), __builtin_bit_cast(float, w.y & 0xffff0000u)};
;                             x1 = (f32x4){__builtin_bit_cast(float, w.z << 16), __builtin_bit_cast(float, w.z & 0xffff0000u), __builtin_bit_cast(float, w.w << 16), __builtin_bit_cast(float, w.w & 0xffff0000u)}; }
;                         acc[ai][bj][m][0] = x0 + vg[bj][0] * (acc[ai][bj][m][0] * rs); acc[ai][bj][m][1] = x1 + vg[bj][1] * (acc[ai][bj][m][1] * rs); }
	v_pk_mul_f32 v[76:77], v[76:77], v[154:155] op_sel_hi:[1,0]
	v_pk_mul_f32 v[68:69], v[68:69], v[154:155] op_sel_hi:[1,0]
	v_pk_fma_f32 v[76:77], v[140:141], v[76:77], v[152:153]
	v_lshlrev_b32_e32 v152, 16, v148
	v_and_b32_e32 v153, 0xffff0000, v148
	v_lshlrev_b32_e32 v148, 16, v149
	v_and_b32_e32 v149, 0xffff0000, v149
	v_pk_fma_f32 v[68:69], v[132:133], v[68:69], v[148:149]
	v_add_u32_e32 v148, s23, v185
	v_and_b32_e32 v157, 0xffff0000, v150
	v_lshlrev_b32_e32 v150, 16, v151
	v_and_b32_e32 v151, 0xffff0000, v151
	v_pk_mul_f32 v[80:81], v[80:81], v[154:155] op_sel_hi:[1,0]
	v_add_u32_e32 v162, 0x80, v148
	v_pk_mul_f32 v[78:79], v[78:79], v[154:155] op_sel_hi:[1,0]
	v_pk_fma_f32 v[80:81], v[144:145], v[80:81], v[150:151]
	v_pk_mul_f32 v[74:75], v[74:75], v[154:155] op_sel_hi:[1,0]
	v_lshlrev_b32_e32 v150, 16, v146
	v_and_b32_e32 v151, 0xffff0000, v146
	v_lshlrev_b32_e32 v146, 16, v147
	v_and_b32_e32 v147, 0xffff0000, v147
	v_pk_mul_f32 v[72:73], v[72:73], v[154:155] op_sel_hi:[1,0]
	v_pk_mul_f32 v[70:71], v[70:71], v[154:155] op_sel_hi:[1,0]
	v_pk_mul_f32 v[66:67], v[66:67], v[154:155] op_sel_hi:[1,0]
	v_ashrrev_i32_e32 v163, 31, v162
	v_pk_fma_f32 v[78:79], v[142:143], v[78:79], v[156:157]
	v_pk_fma_f32 v[74:75], v[138:139], v[74:75], v[158:159]
	v_pk_fma_f32 v[70:71], v[134:135], v[70:71], v[150:151]
	v_pk_fma_f32 v[72:73], v[136:137], v[72:73], v[146:147]
	v_pk_fma_f32 v[66:67], v[130:131], v[66:67], v[152:153]
	v_lshlrev_b64 v[146:147], 12, v[162:163]
	v_lshl_add_u64 v[146:147], v[178:179], 0, v[146:147]
	global_load_dwordx4 v[164:167], v[146:147], off
	global_load_dwordx4 v[168:171], v[146:147], off offset:256
	v_add_u32_e32 v146, 0x90, v148
	v_ashrrev_i32_e32 v147, 31, v146
	v_lshlrev_b64 v[146:147], 12, v[146:147]
	v_lshl_add_u64 v[146:147], v[178:179], 0, v[146:147]
	global_load_dwordx4 v[172:175], v[146:147], off
	global_load_dwordx4 v[200:203], v[146:147], off offset:256
	v_add_u32_e32 v146, 0xa0, v148
	v_ashrrev_i32_e32 v147, 31, v146
	v_lshlrev_b64 v[146:147], 12, v[146:147]
	v_lshl_add_u64 v[146:147], v[178:179], 0, v[146:147]
	global_load_dwordx4 v[158:161], v[146:147], off
	global_load_dwordx4 v[154:157], v[146:147], off offset:256
	v_add_u32_e32 v146, 0xb0, v148
	v_ashrrev_i32_e32 v147, 31, v146
	v_lshlrev_b64 v[146:147], 12, v[146:147]
	v_lshl_add_u64 v[146:147], v[178:179], 0, v[146:147]
	global_load_dwordx4 v[150:153], v[146:147], off
	s_nop 0
	global_load_dwordx4 v[146:149], v[146:147], off offset:256
	ds_read_b32 v176, v186 offset:4608
	s_waitcnt lgkmcnt(0)
	v_pk_mul_f32 v[64:65], v[64:65], v[176:177] op_sel_hi:[1,0]
	v_pk_mul_f32 v[60:61], v[60:61], v[176:177] op_sel_hi:[1,0]
	v_pk_mul_f32 v[62:63], v[62:63], v[176:177] op_sel_hi:[1,0]
	v_pk_mul_f32 v[58:59], v[58:59], v[176:177] op_sel_hi:[1,0]
	v_pk_mul_f32 v[54:55], v[54:55], v[176:177] op_sel_hi:[1,0]
	v_pk_mul_f32 v[56:57], v[56:57], v[176:177] op_sel_hi:[1,0]
	v_pk_mul_f32 v[50:51], v[50:51], v[176:177] op_sel_hi:[1,0]
	v_pk_mul_f32 v[52:53], v[52:53], v[176:177] op_sel_hi:[1,0]
	s_waitcnt vmcnt(7)
	v_lshlrev_b32_e32 v192, 16, v164
	v_and_b32_e32 v193, 0xffff0000, v164
	v_lshlrev_b32_e32 v164, 16, v165
	v_and_b32_e32 v165, 0xffff0000, v165
	v_lshlrev_b32_e32 v204, 16, v166
	v_and_b32_e32 v205, 0xffff0000, v166
	v_lshlrev_b32_e32 v166, 16, v167
	v_and_b32_e32 v167, 0xffff0000, v167
	v_pk_fma_f32 v[64:65], v[144:145], v[64:65], v[164:165]
	v_pk_fma_f32 v[60:61], v[140:141], v[60:61], v[166:167]
	s_waitcnt vmcnt(6)
	v_lshlrev_b32_e32 v164, 16, v168
	v_and_b32_e32 v165, 0xffff0000, v168
	v_lshlrev_b32_e32 v166, 16, v169
	v_and_b32_e32 v167, 0xffff0000, v169
	v_lshlrev_b32_e32 v168, 16, v170
	v_and_b32_e32 v169, 0xffff0000, v170
	v_lshlrev_b32_e32 v170, 16, v171
	v_and_b32_e32 v171, 0xffff0000, v171
	v_pk_fma_f32 v[62:63], v[142:143], v[62:63], v[192:193]
	v_pk_fma_f32 v[58:59], v[138:139], v[58:59], v[204:205]
	v_pk_fma_f32 v[56:57], v[136:137], v[56:57], v[166:167]
	v_pk_fma_f32 v[54:55], v[134:135], v[54:55], v[164:165]
	v_pk_fma_f32 v[52:53], v[132:133], v[52:53], v[170:171]
	v_pk_fma_f32 v[50:51], v[130:131], v[50:51], v[168:169]
	s_waitcnt vmcnt(5)
	v_lshlrev_b32_e32 v166, 16, v172
	ds_read_b32 v164, v186 offset:4672
	v_and_b32_e32 v167, 0xffff0000, v172
	v_lshlrev_b32_e32 v168, 16, v173
	v_and_b32_e32 v169, 0xffff0000, v173
	v_lshlrev_b32_e32 v170, 16, v174
	v_and_b32_e32 v171, 0xffff0000, v174
	v_lshlrev_b32_e32 v172, 16, v175
	v_and_b32_e32 v173, 0xffff0000, v175
	s_waitcnt lgkmcnt(0)
	v_pk_mul_f32 v[46:47], v[46:47], v[164:165] op_sel_hi:[1,0]
	v_pk_mul_f32 v[48:49], v[48:49], v[164:165] op_sel_hi:[1,0]
	v_pk_mul_f32 v[42:43], v[42:43], v[164:165] op_sel_hi:[1,0]
	v_pk_mul_f32 v[44:45], v[44:45], v[164:165] op_sel_hi:[1,0]
	v_pk_fma_f32 v[48:49], v[144:145], v[48:49], v[168:169]
	v_pk_fma_f32 v[46:47], v[142:143], v[46:47], v[166:167]
	v_pk_fma_f32 v[44:45], v[140:141], v[44:45], v[172:173]
	v_pk_fma_f32 v[42:43], v[138:139], v[42:43], v[170:171]
	s_waitcnt vmcnt(4)
	v_lshlrev_b32_e32 v166, 16, v200
	v_and_b32_e32 v167, 0xffff0000, v200
	v_lshlrev_b32_e32 v168, 16, v201
	v_and_b32_e32 v169, 0xffff0000, v201
	v_lshlrev_b32_e32 v170, 16, v202
	v_and_b32_e32 v171, 0xffff0000, v202
	v_lshlrev_b32_e32 v172, 16, v203
	v_and_b32_e32 v173, 0xffff0000, v203
	v_pk_mul_f32 v[38:39], v[38:39], v[164:165] op_sel_hi:[1,0]
	v_pk_mul_f32 v[40:41], v[40:41], v[164:165] op_sel_hi:[1,0]
	v_pk_mul_f32 v[34:35], v[34:35], v[164:165] op_sel_hi:[1,0]
	v_pk_mul_f32 v[36:37], v[36:37], v[164:165] op_sel_hi:[1,0]
	v_pk_fma_f32 v[40:41], v[136:137], v[40:41], v[168:169]
	v_pk_fma_f32 v[38:39], v[134:135], v[38:39], v[166:167]
	v_pk_fma_f32 v[36:37], v[132:133], v[36:37], v[172:173]
	v_pk_fma_f32 v[34:35], v[130:131], v[34:35], v[170:171]
	s_waitcnt vmcnt(3)
;     __device__ __forceinline__ void publish(const f32x4 (&v)[2][2][4][2], const Unit& u, int wr, int wc, int fr, int fq, PG8_LAS unsigned char* lds, int wid, int lane) const {
;     ...
;                 float s = 0.f;
; #pragma unroll
;                 for (int bj = 0; bj < 2; ++bj)
; #pragma unroll
;                     for (int n = 0; n < 2; ++n) { const f32x4 x = v[ai][bj][m][n]; s += (x[0] * x[0] + x[1] * x[1]) + (x[2] * x[2] + x[3] * x[3]); }
;                 s += __shfl_xor(s, 16); s += __shfl_xor(s, 32);
;                 if (fq == 0) P[(ai * HALF + wr * 64 + m * 16 + fr) * 4 + wc] = s;
;     __device__ __forceinline__ void fused(f32x4 (&acc)[2][2][4][2], const Unit& u, int wr, int wc, int fr, int fq, PG8_LAS unsigned char* lds, int wid, int lane) const {
;     ...
;                 for (int m = 0; m < 4; ++m) { const int r = ai * HALF + wr * 64 + m * 16 + fr; const float rs = S[r]; const size_t off = (size_t)(u.pm * BM + r) * 2048 + col0;
; #pragma unroll
;                     for (int bj = 0; bj < 2; ++bj) { f32x4 x0, x1;
;                         if (xin) { x0 = *(const f32x4*)(xin + off + bj * HALF); x1 = *(const f32x4*)(xin + off + bj * HALF + 4); }
;                         else { const u32x4 w = xp[m][bj];
;                             x0 = (f32x4){__builtin_bit_cast(float, w.x << 16), __builtin_bit_cast(float, w.x & 0xffff0000u), __builtin_bit_cast(float, w.y << 16), __builtin_bit_cast(float, w.y & 0xffff0000u)};
;                             x1 = (f32x4){__builtin_bit_cast(float, w.z << 16), __builtin_bit_cast(float, w.z & 0xffff0000u), __builtin_bit_cast(float, w.w << 16), __builtin_bit_cast(float, w.w & 0xffff0000u)}; }
;                         acc[ai][bj][m][0] = x0 + vg[bj][0] * (acc[ai][bj][m][0] * rs); acc[ai][bj][m][1] = x1 + vg[bj][1] * (acc[ai][bj][m][1] * rs); }
;                     asm volatile("" : "+v"(acc[ai][0][m][0]), "+v"(acc[ai][0][m][1]), "+v"(acc[ai][1][m][0]), "+v"(acc[ai][1][m][1]));
;                     if (xin && (m & 1)) asm volatile("" ::: "memory"); }
;             }
;         }
;         if (write_h) bad = st2.run(acc, u, wr, wc, fr, fq, lds, wid, lane) || bad;
	v_lshlrev_b32_e32 v166, 16, v158
	ds_read_b32 v164, v186 offset:4736
	v_and_b32_e32 v167, 0xffff0000, v158
	v_lshlrev_b32_e32 v158, 16, v159
	v_and_b32_e32 v159, 0xffff0000, v159
	v_lshlrev_b32_e32 v168, 16, v160
	v_and_b32_e32 v169, 0xffff0000, v160
	v_lshlrev_b32_e32 v160, 16, v161
	v_and_b32_e32 v161, 0xffff0000, v161
	s_waitcnt lgkmcnt(0)
	v_pk_mul_f32 v[32:33], v[32:33], v[164:165] op_sel_hi:[1,0]
	v_pk_mul_f32 v[28:29], v[28:29], v[164:165] op_sel_hi:[1,0]
	v_pk_mul_f32 v[30:31], v[30:31], v[164:165] op_sel_hi:[1,0]
	v_pk_fma_f32 v[32:33], v[144:145], v[32:33], v[158:159]
	v_pk_mul_f32 v[26:27], v[26:27], v[164:165] op_sel_hi:[1,0]
	v_pk_fma_f32 v[28:29], v[140:141], v[28:29], v[160:161]
	s_waitcnt vmcnt(2)
	v_lshlrev_b32_e32 v158, 16, v154
	v_and_b32_e32 v159, 0xffff0000, v154
	v_lshlrev_b32_e32 v154, 16, v155
	v_and_b32_e32 v155, 0xffff0000, v155
	v_lshlrev_b32_e32 v160, 16, v156
	v_and_b32_e32 v161, 0xffff0000, v156
	v_lshlrev_b32_e32 v156, 16, v157
	v_and_b32_e32 v157, 0xffff0000, v157
	v_pk_mul_f32 v[22:23], v[22:23], v[164:165] op_sel_hi:[1,0]
	v_pk_mul_f32 v[24:25], v[24:25], v[164:165] op_sel_hi:[1,0]
	v_pk_mul_f32 v[18:19], v[18:19], v[164:165] op_sel_hi:[1,0]
	v_pk_mul_f32 v[20:21], v[20:21], v[164:165] op_sel_hi:[1,0]
	v_pk_fma_f32 v[30:31], v[142:143], v[30:31], v[166:167]
	v_pk_fma_f32 v[26:27], v[138:139], v[26:27], v[168:169]
	v_pk_fma_f32 v[24:25], v[136:137], v[24:25], v[154:155]
	v_pk_fma_f32 v[22:23], v[134:135], v[22:23], v[158:159]
	v_pk_fma_f32 v[20:21], v[132:133], v[20:21], v[156:157]
	v_pk_fma_f32 v[18:19], v[130:131], v[18:19], v[160:161]
	s_waitcnt vmcnt(1)
	v_lshlrev_b32_e32 v156, 16, v150
	ds_read_b32 v154, v186 offset:4800
	v_and_b32_e32 v157, 0xffff0000, v150
	v_lshlrev_b32_e32 v150, 16, v151
	v_and_b32_e32 v151, 0xffff0000, v151
	v_lshlrev_b32_e32 v158, 16, v152
	s_waitcnt lgkmcnt(0)
	v_pk_mul_f32 v[14:15], v[14:15], v[154:155] op_sel_hi:[1,0]
	v_and_b32_e32 v159, 0xffff0000, v152
	v_lshlrev_b32_e32 v152, 16, v153
	v_and_b32_e32 v153, 0xffff0000, v153
	v_pk_mul_f32 v[16:17], v[16:17], v[154:155] op_sel_hi:[1,0]
	v_pk_fma_f32 v[14:15], v[142:143], v[14:15], v[156:157]
	v_pk_mul_f32 v[10:11], v[10:11], v[154:155] op_sel_hi:[1,0]
	v_pk_mul_f32 v[12:13], v[12:13], v[154:155] op_sel_hi:[1,0]
	s_waitcnt vmcnt(0)
	v_lshlrev_b32_e32 v142, 16, v148
	v_and_b32_e32 v143, 0xffff0000, v148
	v_pk_mul_f32 v[2:3], v[2:3], v[154:155] op_sel_hi:[1,0]
	v_pk_fma_f32 v[16:17], v[144:145], v[16:17], v[150:151]
	v_pk_fma_f32 v[12:13], v[140:141], v[12:13], v[152:153]
	v_pk_fma_f32 v[10:11], v[138:139], v[10:11], v[158:159]
	v_lshlrev_b32_e32 v138, 16, v146
	v_and_b32_e32 v139, 0xffff0000, v146
	v_lshlrev_b32_e32 v140, 16, v147
	v_and_b32_e32 v141, 0xffff0000, v147
	v_lshlrev_b32_e32 v144, 16, v149
	v_and_b32_e32 v145, 0xffff0000, v149
	v_pk_mul_f32 v[6:7], v[6:7], v[154:155] op_sel_hi:[1,0]
	v_pk_mul_f32 v[8:9], v[8:9], v[154:155] op_sel_hi:[1,0]
	v_pk_mul_f32 v[4:5], v[4:5], v[154:155] op_sel_hi:[1,0]
	v_pk_fma_f32 v[2:3], v[130:131], v[2:3], v[142:143]
	v_cndmask_b32_e64 v130, 0, 1, s[12:13]
	v_pk_fma_f32 v[8:9], v[136:137], v[8:9], v[140:141]
	v_pk_fma_f32 v[6:7], v[134:135], v[6:7], v[138:139]
	v_pk_fma_f32 v[4:5], v[132:133], v[4:5], v[144:145]
	v_cmp_ne_u32_e64 s[38:39], 1, v130
	s_cbranch_vccnz .LBB0_2417
	v_mul_f32_e32 v130, v127, v127
	v_mul_f32_e32 v131, v129, v129
	v_fmac_f32_e32 v130, v126, v126
	v_fmac_f32_e32 v131, v128, v128
	v_add_f32_e32 v130, v130, v131
	v_mul_f32_e32 v131, v123, v123
	v_mul_f32_e32 v132, v125, v125
	v_fmac_f32_e32 v131, v122, v122
	v_fmac_f32_e32 v132, v124, v124
	v_add_f32_e32 v131, v131, v132
	v_add_f32_e32 v130, v130, v131
	v_mul_f32_e32 v131, v119, v119
	v_mul_f32_e32 v132, v121, v121
	v_fmac_f32_e32 v131, v118, v118
	v_fmac_f32_e32 v132, v120, v120
	v_add_f32_e32 v131, v131, v132
	v_add_f32_e32 v130, v131, v130
	v_mul_f32_e32 v131, v115, v115
	v_mul_f32_e32 v132, v117, v117
	v_fmac_f32_e32 v131, v114, v114
	v_fmac_f32_e32 v132, v116, v116
	v_add_f32_e32 v131, v131, v132
	v_add_f32_e32 v130, v131, v130
	v_mov_b32_e32 v131, v130
	s_nop 1
	v_permlane16_swap_b32_e32 v130, v131
	v_add_f32_e32 v130, v130, v131
	v_mov_b32_e32 v131, v130
	s_nop 1
	v_permlane32_swap_b32_e32 v130, v131
	s_and_saveexec_b64 s[4:5], s[40:41]
	s_cbranch_execz .LBB0_2378
	s_lshl_b32 s6, s49, 10
	s_add_i32 s6, s21, s6
	v_lshl_add_u32 v132, v185, 4, s6
	s_waitcnt lgkmcnt(0)
	v_add_f32_e32 v130, v130, v131
	ds_write_b32 v132, v130
.LBB0_2378:
	s_or_b64 exec, exec, s[4:5]
	v_mul_f32_e32 v130, v111, v111
	s_waitcnt lgkmcnt(0)
	v_mul_f32_e32 v131, v113, v113
	v_fmac_f32_e32 v130, v110, v110
	v_fmac_f32_e32 v131, v112, v112
	v_add_f32_e32 v130, v130, v131
	v_mul_f32_e32 v131, v107, v107
	v_mul_f32_e32 v132, v109, v109
	v_fmac_f32_e32 v131, v106, v106
	v_fmac_f32_e32 v132, v108, v108
	v_add_f32_e32 v131, v131, v132
	v_add_f32_e32 v130, v130, v131
	v_mul_f32_e32 v131, v103, v103
	v_mul_f32_e32 v132, v105, v105
	v_fmac_f32_e32 v131, v102, v102
	v_fmac_f32_e32 v132, v104, v104
	v_add_f32_e32 v131, v131, v132
	v_add_f32_e32 v130, v131, v130
	v_mul_f32_e32 v131, v99, v99
	v_mul_f32_e32 v132, v101, v101
	v_fmac_f32_e32 v131, v98, v98
	v_fmac_f32_e32 v132, v100, v100
	v_add_f32_e32 v131, v131, v132
	v_add_f32_e32 v130, v131, v130
	v_mov_b32_e32 v131, v130
	s_nop 1
	v_permlane16_swap_b32_e32 v130, v131
	v_add_f32_e32 v130, v130, v131
	v_mov_b32_e32 v131, v130
	s_nop 1
	v_permlane32_swap_b32_e32 v130, v131
	s_and_saveexec_b64 s[4:5], s[40:41]
	s_cbranch_execz .LBB0_2380
	s_lshl_b32 s6, s49, 10
	s_add_i32 s6, s21, s6
	v_lshl_add_u32 v132, v185, 4, s6
	s_waitcnt lgkmcnt(0)
	v_add_f32_e32 v130, v130, v131
	ds_write_b32 v132, v130 offset:256
;     __device__ __forceinline__ void publish(const f32x4 (&v)[2][2][4][2], const Unit& u, int wr, int wc, int fr, int fq, PG8_LAS unsigned char* lds, int wid, int lane) const {
;     ...
;                 float s = 0.f;
; #pragma unroll
;                 for (int bj = 0; bj < 2; ++bj)
; #pragma unroll
;                     for (int n = 0; n < 2; ++n) { const f32x4 x = v[ai][bj][m][n]; s += (x[0] * x[0] + x[1] * x[1]) + (x[2] * x[2] + x[3] * x[3]); }
;                 s += __shfl_xor(s, 16); s += __shfl_xor(s, 32);
;                 if (fq == 0) P[(ai * HALF + wr * 64 + m * 16 + fr) * 4 + wc] = s;
.LBB0_2380:
	s_or_b64 exec, exec, s[4:5]
	v_mul_f32_e32 v130, v95, v95
	s_waitcnt lgkmcnt(0)
	v_mul_f32_e32 v131, v97, v97
	v_fmac_f32_e32 v130, v94, v94
	v_fmac_f32_e32 v131, v96, v96
	v_add_f32_e32 v130, v130, v131
	v_mul_f32_e32 v131, v91, v91
	v_mul_f32_e32 v132, v93, v93
	v_fmac_f32_e32 v131, v90, v90
	v_fmac_f32_e32 v132, v92, v92
	v_add_f32_e32 v131, v131, v132
	v_add_f32_e32 v130, v130, v131
	v_mul_f32_e32 v131, v87, v87
	v_mul_f32_e32 v132, v89, v89
	v_fmac_f32_e32 v131, v86, v86
	v_fmac_f32_e32 v132, v88, v88
	v_add_f32_e32 v131, v131, v132
	v_add_f32_e32 v130, v131, v130
	v_mul_f32_e32 v131, v83, v83
	v_mul_f32_e32 v132, v85, v85
	v_fmac_f32_e32 v131, v82, v82
	v_fmac_f32_e32 v132, v84, v84
	v_add_f32_e32 v131, v131, v132
	v_add_f32_e32 v130, v131, v130
	v_mov_b32_e32 v131, v130
	s_nop 1
	v_permlane16_swap_b32_e32 v130, v131
	v_add_f32_e32 v130, v130, v131
	v_mov_b32_e32 v131, v130
	s_nop 1
	v_permlane32_swap_b32_e32 v130, v131
	s_and_saveexec_b64 s[4:5], s[40:41]
	s_cbranch_execz .LBB0_2382
	s_lshl_b32 s6, s49, 10
	s_add_i32 s6, s21, s6
	v_lshl_add_u32 v132, v185, 4, s6
	s_waitcnt lgkmcnt(0)
	v_add_f32_e32 v130, v130, v131
	ds_write_b32 v132, v130 offset:512
.LBB0_2382:
	s_or_b64 exec, exec, s[4:5]
	v_mul_f32_e32 v130, v79, v79
	s_waitcnt lgkmcnt(0)
	v_mul_f32_e32 v131, v81, v81
	v_fmac_f32_e32 v130, v78, v78
	v_fmac_f32_e32 v131, v80, v80
	v_add_f32_e32 v130, v130, v131
	v_mul_f32_e32 v131, v75, v75
	v_mul_f32_e32 v132, v77, v77
	v_fmac_f32_e32 v131, v74, v74
	v_fmac_f32_e32 v132, v76, v76
	v_add_f32_e32 v131, v131, v132
	v_add_f32_e32 v130, v130, v131
	v_mul_f32_e32 v131, v71, v71
	v_mul_f32_e32 v132, v73, v73
	v_fmac_f32_e32 v131, v70, v70
	v_fmac_f32_e32 v132, v72, v72
	v_add_f32_e32 v131, v131, v132
	v_add_f32_e32 v130, v131, v130
	v_mul_f32_e32 v131, v67, v67
	v_mul_f32_e32 v132, v69, v69
	v_fmac_f32_e32 v131, v66, v66
	v_fmac_f32_e32 v132, v68, v68
	v_add_f32_e32 v131, v131, v132
	v_add_f32_e32 v130, v131, v130
	v_mov_b32_e32 v131, v130
	s_nop 1
	v_permlane16_swap_b32_e32 v130, v131
	v_add_f32_e32 v130, v130, v131
	v_mov_b32_e32 v131, v130
	s_nop 1
	v_permlane32_swap_b32_e32 v130, v131
	s_and_saveexec_b64 s[4:5], s[40:41]
	s_cbranch_execz .LBB0_2384
	s_lshl_b32 s6, s49, 10
	s_add_i32 s6, s21, s6
	v_lshl_add_u32 v132, v185, 4, s6
	s_waitcnt lgkmcnt(0)
	v_add_f32_e32 v130, v130, v131
	ds_write_b32 v132, v130 offset:768
.LBB0_2384:
	s_or_b64 exec, exec, s[4:5]
	v_mul_f32_e32 v130, v63, v63
	s_waitcnt lgkmcnt(0)
	v_mul_f32_e32 v131, v65, v65
	v_fmac_f32_e32 v130, v62, v62
	v_fmac_f32_e32 v131, v64, v64
	v_add_f32_e32 v130, v130, v131
	v_mul_f32_e32 v131, v59, v59
	v_mul_f32_e32 v132, v61, v61
	v_fmac_f32_e32 v131, v58, v58
	v_fmac_f32_e32 v132, v60, v60
	v_add_f32_e32 v131, v131, v132
	v_add_f32_e32 v130, v130, v131
	v_mul_f32_e32 v131, v55, v55
	v_mul_f32_e32 v132, v57, v57
	v_fmac_f32_e32 v131, v54, v54
	v_fmac_f32_e32 v132, v56, v56
	v_add_f32_e32 v131, v131, v132
	v_add_f32_e32 v130, v131, v130
	v_mul_f32_e32 v131, v51, v51
	v_mul_f32_e32 v132, v53, v53
	v_fmac_f32_e32 v131, v50, v50
	v_fmac_f32_e32 v132, v52, v52
	v_add_f32_e32 v131, v131, v132
	v_add_f32_e32 v130, v131, v130
	v_mov_b32_e32 v131, v130
	s_nop 1
	v_permlane16_swap_b32_e32 v130, v131
	v_add_f32_e32 v130, v130, v131
	v_mov_b32_e32 v131, v130
	s_nop 1
	v_permlane32_swap_b32_e32 v130, v131
	s_and_saveexec_b64 s[4:5], s[40:41]
	s_cbranch_execz .LBB0_2386
	s_lshl_b32 s6, s49, 10
	s_add_i32 s6, s21, s6
	v_lshl_add_u32 v132, v185, 4, s6
	s_waitcnt lgkmcnt(0)
	v_add_f32_e32 v130, v130, v131
	ds_write_b32 v132, v130 offset:2048
;     __device__ __forceinline__ void publish(const f32x4 (&v)[2][2][4][2], const Unit& u, int wr, int wc, int fr, int fq, PG8_LAS unsigned char* lds, int wid, int lane) const {
;     ...
;                 float s = 0.f;
; #pragma unroll
;                 for (int bj = 0; bj < 2; ++bj)
; #pragma unroll
;                     for (int n = 0; n < 2; ++n) { const f32x4 x = v[ai][bj][m][n]; s += (x[0] * x[0] + x[1] * x[1]) + (x[2] * x[2] + x[3] * x[3]); }
;                 s += __shfl_xor(s, 16); s += __shfl_xor(s, 32);
;                 if (fq == 0) P[(ai * HALF + wr * 64 + m * 16 + fr) * 4 + wc] = s;
.LBB0_2386:
	s_or_b64 exec, exec, s[4:5]
	v_mul_f32_e32 v130, v47, v47
	s_waitcnt lgkmcnt(0)
	v_mul_f32_e32 v131, v49, v49
	v_fmac_f32_e32 v130, v46, v46
	v_fmac_f32_e32 v131, v48, v48
	v_add_f32_e32 v130, v130, v131
	v_mul_f32_e32 v131, v43, v43
	v_mul_f32_e32 v132, v45, v45
	v_fmac_f32_e32 v131, v42, v42
	v_fmac_f32_e32 v132, v44, v44
	v_add_f32_e32 v131, v131, v132
	v_add_f32_e32 v130, v130, v131
	v_mul_f32_e32 v131, v39, v39
	v_mul_f32_e32 v132, v41, v41
	v_fmac_f32_e32 v131, v38, v38
	v_fmac_f32_e32 v132, v40, v40
	v_add_f32_e32 v131, v131, v132
	v_add_f32_e32 v130, v131, v130
	v_mul_f32_e32 v131, v35, v35
	v_mul_f32_e32 v132, v37, v37
	v_fmac_f32_e32 v131, v34, v34
	v_fmac_f32_e32 v132, v36, v36
	v_add_f32_e32 v131, v131, v132
	v_add_f32_e32 v130, v131, v130
	v_mov_b32_e32 v131, v130
	s_nop 1
	v_permlane16_swap_b32_e32 v130, v131
	v_add_f32_e32 v130, v130, v131
	v_mov_b32_e32 v131, v130
	s_nop 1
	v_permlane32_swap_b32_e32 v130, v131
	s_and_saveexec_b64 s[4:5], s[40:41]
	s_cbranch_execz .LBB0_2388
	s_lshl_b32 s6, s49, 10
	s_add_i32 s6, s21, s6
	v_lshl_add_u32 v132, v185, 4, s6
	s_waitcnt lgkmcnt(0)
	v_add_f32_e32 v130, v130, v131
	ds_write_b32 v132, v130 offset:2304
.LBB0_2388:
	s_or_b64 exec, exec, s[4:5]
	v_mul_f32_e32 v130, v31, v31
	s_waitcnt lgkmcnt(0)
	v_mul_f32_e32 v131, v33, v33
	v_fmac_f32_e32 v130, v30, v30
	v_fmac_f32_e32 v131, v32, v32
	v_add_f32_e32 v130, v130, v131
	v_mul_f32_e32 v131, v27, v27
	v_mul_f32_e32 v132, v29, v29
	v_fmac_f32_e32 v131, v26, v26
	v_fmac_f32_e32 v132, v28, v28
	v_add_f32_e32 v131, v131, v132
	v_add_f32_e32 v130, v130, v131
	v_mul_f32_e32 v131, v23, v23
	v_mul_f32_e32 v132, v25, v25
	v_fmac_f32_e32 v131, v22, v22
	v_fmac_f32_e32 v132, v24, v24
	v_add_f32_e32 v131, v131, v132
	v_add_f32_e32 v130, v131, v130
	v_mul_f32_e32 v131, v19, v19
	v_mul_f32_e32 v132, v21, v21
	v_fmac_f32_e32 v131, v18, v18
	v_fmac_f32_e32 v132, v20, v20
	v_add_f32_e32 v131, v131, v132
	v_add_f32_e32 v130, v131, v130
	v_mov_b32_e32 v131, v130
	s_nop 1
	v_permlane16_swap_b32_e32 v130, v131
	v_add_f32_e32 v130, v130, v131
	v_mov_b32_e32 v131, v130
	s_nop 1
	v_permlane32_swap_b32_e32 v130, v131
	s_and_saveexec_b64 s[4:5], s[40:41]
	s_cbranch_execz .LBB0_2390
	s_lshl_b32 s6, s49, 10
	s_add_i32 s6, s21, s6
	v_lshl_add_u32 v132, v185, 4, s6
	s_waitcnt lgkmcnt(0)
	v_add_f32_e32 v130, v130, v131
	ds_write_b32 v132, v130 offset:2560
.LBB0_2390:
	s_or_b64 exec, exec, s[4:5]
	v_mul_f32_e32 v130, v15, v15
	s_waitcnt lgkmcnt(0)
	v_mul_f32_e32 v131, v17, v17
	v_fmac_f32_e32 v130, v14, v14
	v_fmac_f32_e32 v131, v16, v16
	v_add_f32_e32 v130, v130, v131
	v_mul_f32_e32 v131, v11, v11
	v_mul_f32_e32 v132, v13, v13
	v_fmac_f32_e32 v131, v10, v10
	v_fmac_f32_e32 v132, v12, v12
	v_add_f32_e32 v131, v131, v132
	v_add_f32_e32 v130, v130, v131
	v_mul_f32_e32 v131, v7, v7
	v_mul_f32_e32 v132, v9, v9
	v_fmac_f32_e32 v131, v6, v6
	v_fmac_f32_e32 v132, v8, v8
	v_add_f32_e32 v131, v131, v132
	v_add_f32_e32 v130, v131, v130
	v_mul_f32_e32 v131, v3, v3
	v_mul_f32_e32 v132, v5, v5
	v_fmac_f32_e32 v131, v2, v2
	v_fmac_f32_e32 v132, v4, v4
	v_add_f32_e32 v131, v131, v132
	v_add_f32_e32 v130, v131, v130
	v_mov_b32_e32 v131, v130
	s_nop 1
	v_permlane16_swap_b32_e32 v130, v131
	v_add_f32_e32 v130, v130, v131
	v_mov_b32_e32 v131, v130
	s_nop 1
	v_permlane32_swap_b32_e32 v130, v131
	s_and_saveexec_b64 s[4:5], s[40:41]
	s_cbranch_execz .LBB0_2392
	s_lshl_b32 s6, s49, 10
	s_add_i32 s21, s21, s6
	v_lshl_add_u32 v132, v185, 4, s21
	s_waitcnt lgkmcnt(0)
	v_add_f32_e32 v130, v130, v131
	ds_write_b32 v132, v130 offset:2816
